# 4-phase K-loop in all 8 GEMM instances incl. P3 with peel; prologue vmcnt(4)->vmcnt(0) closes the first-iteration Bs[0][1] visibility hole
# baseline (speedup 1.0000x reference)
.LBB0_563:
	s_add_u32 s0, s30, 0x1b00000
	s_addc_u32 s1, s31, 0
	s_mov_b64 s[4:5], 0x80
	s_add_u32 s8, s34, 0x40080
	v_lshl_add_u64 v[2:3], v[2:3], 0, s[4:5]
	s_addc_u32 s9, s35, 0
	s_add_i32 m0, s53, 0x18000
	v_lshl_add_u64 v[4:5], v[4:5], 0, s[4:5]
	s_waitcnt vmcnt(0)
	s_barrier
	global_load_lds_dwordx4 v[2:3], off
	s_add_i32 m0, s53, 0x1a000
	s_add_i32 s68, s53, 0x8000
	v_lshl_add_u64 v[6:7], v[6:7], 0, s[4:5]
	global_load_lds_dwordx4 v[4:5], off
	s_mov_b32 m0, s68
	s_add_i32 s69, s53, 0xa000
	v_lshl_add_u64 v[8:9], v[8:9], 0, s[4:5]
	global_load_lds_dwordx4 v[6:7], off
	s_mov_b32 m0, s69
	s_waitcnt vmcnt(0)
	v_lshl_add_u64 v[14:15], s[8:9], 0, v[134:135]
	global_load_lds_dwordx4 v[8:9], off
	s_add_i32 m0, s53, 0x1c000
	v_lshl_add_u64 v[16:17], s[8:9], 0, v[130:131]
	global_load_lds_dwordx4 v[14:15], off
	s_add_i32 m0, s53, 0x1e000
	v_lshlrev_b32_e32 v3, 4, v1
	global_load_lds_dwordx4 v[16:17], off
	v_lshlrev_b32_e32 v4, 6, v170
	s_movk_i32 s7, 0x3c0
	v_lshlrev_b32_e32 v6, 2, v148
	v_and_or_b32 v4, v4, s7, v3
	v_lshlrev_b32_e32 v5, 2, v170
	s_sext_i32_i16 s15, s2
	s_and_b32 s2, s6, 3
	v_lshl_or_b32 v149, s3, 6, v148
	v_lshl_or_b32 v3, v148, 6, v3
	s_lshl_b32 s3, s3, 13
	v_and_b32_e32 v6, 32, v6
	v_and_b32_e32 v5, 32, v5
	v_bitop3_b32 v3, v3, s3, v6 bitop3:0xde
	s_lshl_b32 s3, s2, 12
	v_bitop3_b32 v150, s3, v4, v5 bitop3:0xf6
	v_lshlrev_b32_e32 v4, 8, v170
	v_and_b32_e32 v4, 0x38000, v4
	v_lshlrev_b32_e32 v5, 11, v13
	v_or3_b32 v4, v11, v4, v5
	v_add_u32_e32 v140, v4, v12
	v_lshlrev_b32_e32 v4, 4, v10
	v_lshlrev_b32_e32 v2, 3, v1
	s_waitcnt vmcnt(6)
	v_and_b32_e32 v4, 0x78000, v4
	v_lshl_or_b32 v2, s2, 5, v2
	v_or3_b32 v4, v11, v4, v5
	s_add_i32 s72, 0, 0x10000
	s_add_i32 s73, 0, 0x14000
	s_ashr_i32 s70, s22, 31
	s_mov_b32 s71, s22
	v_mov_b32_e32 v141, v139
	v_add_u32_e32 v142, v4, v12
	v_mov_b32_e32 v143, v139
	v_mov_b64_e32 v[144:145], 0xc60
	v_mov_b64_e32 v[146:147], 0xc5f
	v_add_u32_e32 v151, s72, v150
	v_add_u32_e32 v152, 0, v3
	v_add_u32_e32 v153, s73, v150
	s_movk_i32 s74, 0x1600
	v_lshlrev_b32_e32 v138, 1, v2
	s_barrier

.LBB0_809:
	s_add_u32 s71, s30, 0x13d00000
	s_addc_u32 s72, s31, 0
	s_add_u32 s12, s30, 0x1b800000
	s_addc_u32 s13, s31, 0
	s_add_u32 s14, s30, 0x13980000
	s_mov_b64 s[16:17], 0x80
	s_addc_u32 s15, s31, 0
	s_and_b32 s73, s1, 3
	s_add_i32 m0, s57, 0x18000
	v_lshl_add_u64 v[2:3], v[2:3], 0, s[16:17]
	s_lshl_b32 s1, s0, 13
	s_lshl_b32 s6, s73, 12
	s_waitcnt vmcnt(0)
	s_barrier
	global_load_lds_dwordx4 v[2:3], off
	v_lshl_add_u64 v[2:3], v[4:5], 0, s[16:17]
	s_add_i32 m0, s57, 0x1a000
	s_add_i32 s74, s57, 0x8000
	s_add_i32 s75, s57, 0xa000
	global_load_lds_dwordx4 v[2:3], off
	v_lshl_add_u64 v[2:3], v[8:9], 0, s[16:17]
	s_mov_b32 m0, s74
	s_add_u32 s4, s8, 0xb0080
	global_load_lds_dwordx4 v[2:3], off
	v_lshl_add_u64 v[2:3], v[6:7], 0, s[16:17]
	s_mov_b32 m0, s75
	s_addc_u32 s5, s9, 0
	global_load_lds_dwordx4 v[2:3], off
	s_add_i32 m0, s57, 0x1c000
	v_lshl_add_u64 v[2:3], s[4:5], 0, v[176:177]
	global_load_lds_dwordx4 v[2:3], off
	v_lshl_add_u64 v[2:3], s[4:5], 0, v[180:181]
	s_add_i32 m0, s57, 0x1e000
	v_lshlrev_b32_e32 v5, 2, v175
	global_load_lds_dwordx4 v[2:3], off
	v_lshlrev_b32_e32 v2, 3, v183
	v_lshlrev_b32_e32 v3, 4, v183
	v_lshl_or_b32 v182, s73, 5, v2
	v_add_u16_e32 v2, v235, v236
	v_or_b32_e32 v4, v3, v238
	v_lshl_or_b32 v3, v175, 6, v3
	v_and_b32_e32 v5, 32, v5
	s_waitcnt vmcnt(6)
	v_lshrrev_b16_e32 v2, 1, v2
	v_bitop3_b32 v3, v3, s1, v5 bitop3:0xde
	v_bitop3_b32 v240, s6, v4, v237 bitop3:0xf6
	v_mov_b32_e32 v185, 0
	v_add_lshl_u32 v186, v233, v2, 1
	v_add_lshl_u32 v188, v234, v2, 1
	s_add_i32 s77, 0, 0x10000
	s_add_i32 s78, 0, 0x14000
	v_mbcnt_lo_u32_b32 v2, -1, 0
	v_lshl_or_b32 v239, s0, 6, v175
	s_mov_b32 s35, 0
	s_mov_b32 s76, 0x8000
	v_mov_b32_e32 v187, v185
	v_mov_b32_e32 v189, v185
	v_mov_b64_e32 v[190:191], 0x200
	v_mov_b64_e32 v[192:193], 0x1ff
	v_add_u32_e32 v241, s77, v240
	v_add_u32_e32 v242, 0, v3
	v_add_u32_e32 v243, s78, v240
	v_mbcnt_hi_u32_b32 v244, -1, v2
	s_mov_b32 s79, 0
	s_barrier
	s_branch .LBB0_811

.LBB0_821:
	s_add_u32 s0, s10, 0xb0080
	s_addc_u32 s1, s11, 0
	s_add_u32 s10, s8, 0x100
	s_addc_u32 s11, s9, 0
	s_mov_b32 s49, -2
	s_waitcnt lgkmcnt(0)
	ds_read_b128 v[130:133], v241
	ds_read_b128 v[134:137], v241 offset:1024
	ds_read_b128 v[138:141], v241 offset:2048
	ds_read_b128 v[142:145], v241 offset:3072
	s_add_u32 s6, s0, 0xfff50080
	s_addc_u32 s7, s1, -1
	s_cmp_eq_u32 s49, 40
	s_cselect_b32 s9, s39, s7
	s_cselect_b32 s8, s38, s6
	s_cselect_b32 s7, s41, s11
	s_cselect_b32 s6, s40, s10
	v_lshl_add_u64 v[202:203], s[0:1], 0, v[186:187]
	s_add_i32 m0, s57, 0xc000
	ds_read_b128 v[146:149], v242
	ds_read_b128 v[150:153], v242 offset:1024
	ds_read_b128 v[154:157], v242 offset:2048
	ds_read_b128 v[158:161], v242 offset:3072
	ds_read_b128 v[162:165], v242 offset:4096
	ds_read_b128 v[166:169], v242 offset:5120
	ds_read_b128 v[194:197], v242 offset:6144
	ds_read_b128 v[198:201], v242 offset:7168
	global_load_lds_dwordx4 v[202:203], off
	v_lshl_add_u64 v[202:203], s[0:1], 0, v[188:189]
	s_add_i32 m0, s57, 0xe000
	s_nop 0
	global_load_lds_dwordx4 v[202:203], off
	ds_read_b128 v[202:205], v243
	ds_read_b128 v[206:209], v243 offset:1024
	ds_read_b128 v[210:213], v243 offset:2048
	ds_read_b128 v[214:217], v243 offset:3072
	s_waitcnt vmcnt(8)
	s_waitcnt lgkmcnt(0)
	s_setprio 1
	s_barrier
	v_mfma_f32_16x16x32_bf16 v[126:129], v[130:133], v[146:149], 0
	v_mfma_f32_16x16x32_bf16 v[122:125], v[138:141], v[146:149], 0
	v_mfma_f32_16x16x32_bf16 v[110:113], v[130:133], v[154:157], 0
	v_mfma_f32_16x16x32_bf16 v[106:109], v[138:141], v[154:157], 0
	v_mfma_f32_16x16x32_bf16 v[94:97], v[130:133], v[162:165], 0
	v_mfma_f32_16x16x32_bf16 v[90:93], v[138:141], v[162:165], 0
	v_mfma_f32_16x16x32_bf16 v[78:81], v[130:133], v[194:197], 0
	v_mfma_f32_16x16x32_bf16 v[74:77], v[138:141], v[194:197], 0
	v_mfma_f32_16x16x32_bf16 v[126:129], v[134:137], v[150:153], v[126:129]
	v_mfma_f32_16x16x32_bf16 v[122:125], v[142:145], v[150:153], v[122:125]
	v_mfma_f32_16x16x32_bf16 v[110:113], v[134:137], v[158:161], v[110:113]
	v_mfma_f32_16x16x32_bf16 v[106:109], v[142:145], v[158:161], v[106:109]
	v_mfma_f32_16x16x32_bf16 v[94:97], v[134:137], v[166:169], v[94:97]
	v_mfma_f32_16x16x32_bf16 v[90:93], v[142:145], v[166:169], v[90:93]
	v_mfma_f32_16x16x32_bf16 v[78:81], v[134:137], v[198:201], v[78:81]
	v_mfma_f32_16x16x32_bf16 v[74:77], v[142:145], v[198:201], v[74:77]
	v_mfma_f32_16x16x32_bf16 v[118:121], v[202:205], v[146:149], 0
	v_mfma_f32_16x16x32_bf16 v[114:117], v[210:213], v[146:149], 0
	v_mfma_f32_16x16x32_bf16 v[102:105], v[202:205], v[154:157], 0
	v_mfma_f32_16x16x32_bf16 v[98:101], v[210:213], v[154:157], 0
	v_mfma_f32_16x16x32_bf16 v[86:89], v[202:205], v[162:165], 0
	v_mfma_f32_16x16x32_bf16 v[82:85], v[210:213], v[162:165], 0
	v_mfma_f32_16x16x32_bf16 v[70:73], v[202:205], v[194:197], 0
	v_mfma_f32_16x16x32_bf16 v[66:69], v[210:213], v[194:197], 0
	v_mfma_f32_16x16x32_bf16 v[118:121], v[206:209], v[150:153], v[118:121]
	v_mfma_f32_16x16x32_bf16 v[114:117], v[214:217], v[150:153], v[114:117]
	v_mfma_f32_16x16x32_bf16 v[102:105], v[206:209], v[158:161], v[102:105]
	v_mfma_f32_16x16x32_bf16 v[98:101], v[214:217], v[158:161], v[98:101]
	v_mfma_f32_16x16x32_bf16 v[86:89], v[206:209], v[166:169], v[86:89]
	v_mfma_f32_16x16x32_bf16 v[82:85], v[214:217], v[166:169], v[82:85]
	v_mfma_f32_16x16x32_bf16 v[70:73], v[206:209], v[198:201], v[70:73]
	v_mfma_f32_16x16x32_bf16 v[66:69], v[214:217], v[198:201], v[66:69]
	s_barrier
	s_setprio 0
	s_add_i32 s20, s77, s56
	v_lshl_add_u64 v[218:219], s[6:7], 0, v[176:177]
	s_mov_b32 m0, s20
	s_nop 0
	global_load_lds_dwordx4 v[218:219], off
	v_lshl_add_u64 v[220:221], s[6:7], 0, v[180:181]
	s_add_i32 m0, s20, 0x2000
	s_nop 0
	global_load_lds_dwordx4 v[220:221], off
	s_mov_b32 m0, s57
	v_lshl_add_u64 v[222:223], s[8:9], 0, v[172:173]
	ds_read_b128 v[146:149], v242 offset:16384
	ds_read_b128 v[150:153], v242 offset:17408
	ds_read_b128 v[154:157], v242 offset:18432
	ds_read_b128 v[158:161], v242 offset:19456
	ds_read_b128 v[162:165], v242 offset:20480
	ds_read_b128 v[166:169], v242 offset:21504
	ds_read_b128 v[194:197], v242 offset:22528
	ds_read_b128 v[198:201], v242 offset:23552
	global_load_lds_dwordx4 v[222:223], off
	v_lshl_add_u64 v[224:225], s[8:9], 0, v[178:179]
	s_mov_b32 m0, s68
	s_nop 0
	global_load_lds_dwordx4 v[224:225], off
	s_add_u32 s20, s6, 0xb0000
	s_addc_u32 s21, s7, 0
	s_add_i32 s50, s78, s56
	v_lshl_add_u64 v[246:247], s[20:21], 0, v[176:177]
	s_mov_b32 m0, s50
	s_nop 0
	global_load_lds_dwordx4 v[246:247], off
	v_lshl_add_u64 v[246:247], s[20:21], 0, v[180:181]
	s_add_i32 m0, s50, 0x2000
	s_nop 0
	global_load_lds_dwordx4 v[246:247], off
	s_waitcnt vmcnt(8)
	s_waitcnt lgkmcnt(0)
	s_setprio 1
	s_barrier
	v_mfma_f32_16x16x32_bf16 v[62:65], v[130:133], v[146:149], 0
	v_mfma_f32_16x16x32_bf16 v[58:61], v[138:141], v[146:149], 0
	v_mfma_f32_16x16x32_bf16 v[46:49], v[130:133], v[154:157], 0
	v_mfma_f32_16x16x32_bf16 v[42:45], v[138:141], v[154:157], 0
	v_mfma_f32_16x16x32_bf16 v[30:33], v[130:133], v[162:165], 0
	v_mfma_f32_16x16x32_bf16 v[26:29], v[138:141], v[162:165], 0
	v_mfma_f32_16x16x32_bf16 v[14:17], v[130:133], v[194:197], 0
	v_mfma_f32_16x16x32_bf16 v[10:13], v[138:141], v[194:197], 0
	v_mfma_f32_16x16x32_bf16 v[62:65], v[134:137], v[150:153], v[62:65]
	v_mfma_f32_16x16x32_bf16 v[58:61], v[142:145], v[150:153], v[58:61]
	v_mfma_f32_16x16x32_bf16 v[46:49], v[134:137], v[158:161], v[46:49]
	v_mfma_f32_16x16x32_bf16 v[42:45], v[142:145], v[158:161], v[42:45]
	v_mfma_f32_16x16x32_bf16 v[30:33], v[134:137], v[166:169], v[30:33]
	v_mfma_f32_16x16x32_bf16 v[26:29], v[142:145], v[166:169], v[26:29]
	v_mfma_f32_16x16x32_bf16 v[14:17], v[134:137], v[198:201], v[14:17]
	v_mfma_f32_16x16x32_bf16 v[10:13], v[142:145], v[198:201], v[10:13]
	v_mfma_f32_16x16x32_bf16 v[54:57], v[202:205], v[146:149], 0
	v_mfma_f32_16x16x32_bf16 v[50:53], v[210:213], v[146:149], 0
	v_mfma_f32_16x16x32_bf16 v[38:41], v[202:205], v[154:157], 0
	v_mfma_f32_16x16x32_bf16 v[34:37], v[210:213], v[154:157], 0
	v_mfma_f32_16x16x32_bf16 v[22:25], v[202:205], v[162:165], 0
	v_mfma_f32_16x16x32_bf16 v[18:21], v[210:213], v[162:165], 0
	v_mfma_f32_16x16x32_bf16 v[6:9], v[202:205], v[194:197], 0
	v_mfma_f32_16x16x32_bf16 v[2:5], v[210:213], v[194:197], 0
	v_mfma_f32_16x16x32_bf16 v[54:57], v[206:209], v[150:153], v[54:57]
	v_mfma_f32_16x16x32_bf16 v[50:53], v[214:217], v[150:153], v[50:53]
	v_mfma_f32_16x16x32_bf16 v[38:41], v[206:209], v[158:161], v[38:41]
	v_mfma_f32_16x16x32_bf16 v[34:37], v[214:217], v[158:161], v[34:37]
	v_mfma_f32_16x16x32_bf16 v[22:25], v[206:209], v[166:169], v[22:25]
	v_mfma_f32_16x16x32_bf16 v[18:21], v[214:217], v[166:169], v[18:21]
	v_mfma_f32_16x16x32_bf16 v[6:9], v[206:209], v[198:201], v[6:9]
	v_mfma_f32_16x16x32_bf16 v[2:5], v[214:217], v[198:201], v[2:5]
	s_barrier
	s_setprio 0
	s_add_i32 s20, 0, 0x18000
	v_add_u32_e32 v142, s20, v240
	ds_read_b128 v[130:133], v142
	ds_read_b128 v[134:137], v142 offset:1024
	ds_read_b128 v[138:141], v142 offset:2048
	ds_read_b128 v[142:145], v142 offset:3072
	s_add_u32 s8, s8, 0xb0000
	s_addc_u32 s9, s9, 0
	s_mov_b32 m0, s69
	v_lshl_add_u64 v[202:203], s[8:9], 0, v[172:173]
	ds_read_b128 v[146:149], v242 offset:32768
	ds_read_b128 v[150:153], v242 offset:33792
	ds_read_b128 v[154:157], v242 offset:34816
	ds_read_b128 v[158:161], v242 offset:35840
	ds_read_b128 v[162:165], v242 offset:36864
	ds_read_b128 v[166:169], v242 offset:37888
	ds_read_b128 v[194:197], v242 offset:38912
	ds_read_b128 v[198:201], v242 offset:39936
	global_load_lds_dwordx4 v[202:203], off
	v_lshl_add_u64 v[202:203], s[8:9], 0, v[178:179]
	s_mov_b32 m0, s70
	s_nop 0
	global_load_lds_dwordx4 v[202:203], off
	s_add_i32 s8, 0, 0x1c000
	v_add_u32_e32 v184, s8, v240
	ds_read_b128 v[202:205], v184
	ds_read_b128 v[206:209], v184 offset:1024
	ds_read_b128 v[210:213], v184 offset:2048
	ds_read_b128 v[214:217], v184 offset:3072
	s_waitcnt vmcnt(8)
	s_waitcnt lgkmcnt(0)
	s_setprio 1
	s_barrier
	v_mfma_f32_16x16x32_bf16 v[126:129], v[130:133], v[146:149], v[126:129]
	v_mfma_f32_16x16x32_bf16 v[122:125], v[138:141], v[146:149], v[122:125]
	v_mfma_f32_16x16x32_bf16 v[110:113], v[130:133], v[154:157], v[110:113]
	v_mfma_f32_16x16x32_bf16 v[106:109], v[138:141], v[154:157], v[106:109]
	v_mfma_f32_16x16x32_bf16 v[94:97], v[130:133], v[162:165], v[94:97]
	v_mfma_f32_16x16x32_bf16 v[90:93], v[138:141], v[162:165], v[90:93]
	v_mfma_f32_16x16x32_bf16 v[78:81], v[130:133], v[194:197], v[78:81]
	v_mfma_f32_16x16x32_bf16 v[74:77], v[138:141], v[194:197], v[74:77]
	v_mfma_f32_16x16x32_bf16 v[126:129], v[134:137], v[150:153], v[126:129]
	v_mfma_f32_16x16x32_bf16 v[122:125], v[142:145], v[150:153], v[122:125]
	v_mfma_f32_16x16x32_bf16 v[110:113], v[134:137], v[158:161], v[110:113]
	v_mfma_f32_16x16x32_bf16 v[106:109], v[142:145], v[158:161], v[106:109]
	v_mfma_f32_16x16x32_bf16 v[94:97], v[134:137], v[166:169], v[94:97]
	v_mfma_f32_16x16x32_bf16 v[90:93], v[142:145], v[166:169], v[90:93]
	v_mfma_f32_16x16x32_bf16 v[78:81], v[134:137], v[198:201], v[78:81]
	v_mfma_f32_16x16x32_bf16 v[74:77], v[142:145], v[198:201], v[74:77]
	v_mfma_f32_16x16x32_bf16 v[118:121], v[202:205], v[146:149], v[118:121]
	v_mfma_f32_16x16x32_bf16 v[114:117], v[210:213], v[146:149], v[114:117]
	v_mfma_f32_16x16x32_bf16 v[102:105], v[202:205], v[154:157], v[102:105]
	v_mfma_f32_16x16x32_bf16 v[98:101], v[210:213], v[154:157], v[98:101]
	v_mfma_f32_16x16x32_bf16 v[86:89], v[202:205], v[162:165], v[86:89]
	v_mfma_f32_16x16x32_bf16 v[82:85], v[210:213], v[162:165], v[82:85]
	v_mfma_f32_16x16x32_bf16 v[70:73], v[202:205], v[194:197], v[70:73]
	v_mfma_f32_16x16x32_bf16 v[66:69], v[210:213], v[194:197], v[66:69]
	v_mfma_f32_16x16x32_bf16 v[118:121], v[206:209], v[150:153], v[118:121]
	v_mfma_f32_16x16x32_bf16 v[114:117], v[214:217], v[150:153], v[114:117]
	v_mfma_f32_16x16x32_bf16 v[102:105], v[206:209], v[158:161], v[102:105]
	v_mfma_f32_16x16x32_bf16 v[98:101], v[214:217], v[158:161], v[98:101]
	v_mfma_f32_16x16x32_bf16 v[86:89], v[206:209], v[166:169], v[86:89]
	v_mfma_f32_16x16x32_bf16 v[82:85], v[214:217], v[166:169], v[82:85]
	v_mfma_f32_16x16x32_bf16 v[70:73], v[206:209], v[198:201], v[70:73]
	v_mfma_f32_16x16x32_bf16 v[66:69], v[214:217], v[198:201], v[66:69]
	s_barrier
	s_setprio 0
	s_add_i32 s9, s20, s56
	v_lshl_add_u64 v[218:219], v[218:219], 0, s[16:17]
	s_mov_b32 m0, s9
	s_nop 0
	global_load_lds_dwordx4 v[218:219], off
	v_lshl_add_u64 v[218:219], v[220:221], 0, s[16:17]
	s_add_i32 m0, s9, 0x2000
	s_nop 0
	global_load_lds_dwordx4 v[218:219], off
	s_mov_b32 m0, s74
	v_lshl_add_u64 v[218:219], v[222:223], 0, s[16:17]
	ds_read_b128 v[146:149], v242 offset:49152
	ds_read_b128 v[150:153], v242 offset:50176
	ds_read_b128 v[154:157], v242 offset:51200
	ds_read_b128 v[158:161], v242 offset:52224
	ds_read_b128 v[162:165], v242 offset:53248
	ds_read_b128 v[166:169], v242 offset:54272
	ds_read_b128 v[194:197], v242 offset:55296
	ds_read_b128 v[198:201], v242 offset:56320
	global_load_lds_dwordx4 v[218:219], off
	v_lshl_add_u64 v[218:219], v[224:225], 0, s[16:17]
	s_mov_b32 m0, s75
	s_nop 0
	global_load_lds_dwordx4 v[218:219], off
	s_add_u32 s6, s6, 0xb0080
	s_addc_u32 s7, s7, 0
	s_add_i32 s8, s8, s56
	v_lshl_add_u64 v[248:249], s[6:7], 0, v[176:177]
	s_mov_b32 m0, s8
	s_nop 0
	global_load_lds_dwordx4 v[248:249], off
	v_lshl_add_u64 v[248:249], s[6:7], 0, v[180:181]
	s_add_i32 m0, s8, 0x2000
	s_nop 0
	global_load_lds_dwordx4 v[248:249], off
	s_waitcnt vmcnt(8)
	s_waitcnt lgkmcnt(0)
	s_setprio 1
	s_barrier
	v_mfma_f32_16x16x32_bf16 v[62:65], v[130:133], v[146:149], v[62:65]
	v_mfma_f32_16x16x32_bf16 v[58:61], v[138:141], v[146:149], v[58:61]
	v_mfma_f32_16x16x32_bf16 v[46:49], v[130:133], v[154:157], v[46:49]
	v_mfma_f32_16x16x32_bf16 v[42:45], v[138:141], v[154:157], v[42:45]
	v_mfma_f32_16x16x32_bf16 v[30:33], v[130:133], v[162:165], v[30:33]
	v_mfma_f32_16x16x32_bf16 v[26:29], v[138:141], v[162:165], v[26:29]
	v_mfma_f32_16x16x32_bf16 v[14:17], v[130:133], v[194:197], v[14:17]
	v_mfma_f32_16x16x32_bf16 v[10:13], v[138:141], v[194:197], v[10:13]
	v_mfma_f32_16x16x32_bf16 v[62:65], v[134:137], v[150:153], v[62:65]
	v_mfma_f32_16x16x32_bf16 v[58:61], v[142:145], v[150:153], v[58:61]
	v_mfma_f32_16x16x32_bf16 v[46:49], v[134:137], v[158:161], v[46:49]
	v_mfma_f32_16x16x32_bf16 v[42:45], v[142:145], v[158:161], v[42:45]
	v_mfma_f32_16x16x32_bf16 v[30:33], v[134:137], v[166:169], v[30:33]
	v_mfma_f32_16x16x32_bf16 v[26:29], v[142:145], v[166:169], v[26:29]
	v_mfma_f32_16x16x32_bf16 v[14:17], v[134:137], v[198:201], v[14:17]
	v_mfma_f32_16x16x32_bf16 v[10:13], v[142:145], v[198:201], v[10:13]
	v_mfma_f32_16x16x32_bf16 v[54:57], v[202:205], v[146:149], v[54:57]
	v_mfma_f32_16x16x32_bf16 v[50:53], v[210:213], v[146:149], v[50:53]
	v_mfma_f32_16x16x32_bf16 v[38:41], v[202:205], v[154:157], v[38:41]
	v_mfma_f32_16x16x32_bf16 v[34:37], v[210:213], v[154:157], v[34:37]
	v_mfma_f32_16x16x32_bf16 v[22:25], v[202:205], v[162:165], v[22:25]
	v_mfma_f32_16x16x32_bf16 v[18:21], v[210:213], v[162:165], v[18:21]
	v_mfma_f32_16x16x32_bf16 v[6:9], v[202:205], v[194:197], v[6:9]
	v_mfma_f32_16x16x32_bf16 v[2:5], v[210:213], v[194:197], v[2:5]
	v_mfma_f32_16x16x32_bf16 v[54:57], v[206:209], v[150:153], v[54:57]
	v_mfma_f32_16x16x32_bf16 v[50:53], v[214:217], v[150:153], v[50:53]
	v_mfma_f32_16x16x32_bf16 v[38:41], v[206:209], v[158:161], v[38:41]
	v_mfma_f32_16x16x32_bf16 v[34:37], v[214:217], v[158:161], v[34:37]
	v_mfma_f32_16x16x32_bf16 v[22:25], v[206:209], v[166:169], v[22:25]
	v_mfma_f32_16x16x32_bf16 v[18:21], v[214:217], v[166:169], v[18:21]
	v_mfma_f32_16x16x32_bf16 v[6:9], v[206:209], v[198:201], v[6:9]
	v_mfma_f32_16x16x32_bf16 v[2:5], v[214:217], v[198:201], v[2:5]
	s_barrier
	s_setprio 0
	s_add_i32 s49, s49, 2
	s_add_u32 s0, s0, 0x100
	s_addc_u32 s1, s1, 0
	s_add_u32 s10, s10, 0x100
	s_addc_u32 s11, s11, 0
	s_cmp_gt_u32 s49, 41
.LBB0_822:
	ds_read_b128 v[130:133], v241
	ds_read_b128 v[134:137], v241 offset:1024
	ds_read_b128 v[138:141], v241 offset:2048
	ds_read_b128 v[142:145], v241 offset:3072
	s_add_u32 s6, s0, 0xfff50080
	s_addc_u32 s7, s1, -1
	s_cmp_eq_u32 s49, 40
	s_cselect_b32 s9, s39, s7
	s_cselect_b32 s8, s38, s6
	s_cselect_b32 s7, s41, s11
	s_cselect_b32 s6, s40, s10
	v_lshl_add_u64 v[202:203], s[0:1], 0, v[186:187]
	s_add_i32 m0, s57, 0xc000
	ds_read_b128 v[146:149], v242
	ds_read_b128 v[150:153], v242 offset:1024
	ds_read_b128 v[154:157], v242 offset:2048
	ds_read_b128 v[158:161], v242 offset:3072
	ds_read_b128 v[162:165], v242 offset:4096
	ds_read_b128 v[166:169], v242 offset:5120
	ds_read_b128 v[194:197], v242 offset:6144
	ds_read_b128 v[198:201], v242 offset:7168
	global_load_lds_dwordx4 v[202:203], off
	v_lshl_add_u64 v[202:203], s[0:1], 0, v[188:189]
	s_add_i32 m0, s57, 0xe000
	s_nop 0
	global_load_lds_dwordx4 v[202:203], off
	ds_read_b128 v[202:205], v243
	ds_read_b128 v[206:209], v243 offset:1024
	ds_read_b128 v[210:213], v243 offset:2048
	ds_read_b128 v[214:217], v243 offset:3072
	s_waitcnt vmcnt(8)
	s_waitcnt lgkmcnt(0)
	s_setprio 1
	s_barrier
	v_mfma_f32_16x16x32_bf16 v[126:129], v[130:133], v[146:149], v[126:129]
	v_mfma_f32_16x16x32_bf16 v[122:125], v[138:141], v[146:149], v[122:125]
	v_mfma_f32_16x16x32_bf16 v[110:113], v[130:133], v[154:157], v[110:113]
	v_mfma_f32_16x16x32_bf16 v[106:109], v[138:141], v[154:157], v[106:109]
	v_mfma_f32_16x16x32_bf16 v[94:97], v[130:133], v[162:165], v[94:97]
	v_mfma_f32_16x16x32_bf16 v[90:93], v[138:141], v[162:165], v[90:93]
	v_mfma_f32_16x16x32_bf16 v[78:81], v[130:133], v[194:197], v[78:81]
	v_mfma_f32_16x16x32_bf16 v[74:77], v[138:141], v[194:197], v[74:77]
	v_mfma_f32_16x16x32_bf16 v[126:129], v[134:137], v[150:153], v[126:129]
	v_mfma_f32_16x16x32_bf16 v[122:125], v[142:145], v[150:153], v[122:125]
	v_mfma_f32_16x16x32_bf16 v[110:113], v[134:137], v[158:161], v[110:113]
	v_mfma_f32_16x16x32_bf16 v[106:109], v[142:145], v[158:161], v[106:109]
	v_mfma_f32_16x16x32_bf16 v[94:97], v[134:137], v[166:169], v[94:97]
	v_mfma_f32_16x16x32_bf16 v[90:93], v[142:145], v[166:169], v[90:93]
	v_mfma_f32_16x16x32_bf16 v[78:81], v[134:137], v[198:201], v[78:81]
	v_mfma_f32_16x16x32_bf16 v[74:77], v[142:145], v[198:201], v[74:77]
	v_mfma_f32_16x16x32_bf16 v[118:121], v[202:205], v[146:149], v[118:121]
	v_mfma_f32_16x16x32_bf16 v[114:117], v[210:213], v[146:149], v[114:117]
	v_mfma_f32_16x16x32_bf16 v[102:105], v[202:205], v[154:157], v[102:105]
	v_mfma_f32_16x16x32_bf16 v[98:101], v[210:213], v[154:157], v[98:101]
	v_mfma_f32_16x16x32_bf16 v[86:89], v[202:205], v[162:165], v[86:89]
	v_mfma_f32_16x16x32_bf16 v[82:85], v[210:213], v[162:165], v[82:85]
	v_mfma_f32_16x16x32_bf16 v[70:73], v[202:205], v[194:197], v[70:73]
	v_mfma_f32_16x16x32_bf16 v[66:69], v[210:213], v[194:197], v[66:69]
	v_mfma_f32_16x16x32_bf16 v[118:121], v[206:209], v[150:153], v[118:121]
	v_mfma_f32_16x16x32_bf16 v[114:117], v[214:217], v[150:153], v[114:117]
	v_mfma_f32_16x16x32_bf16 v[102:105], v[206:209], v[158:161], v[102:105]
	v_mfma_f32_16x16x32_bf16 v[98:101], v[214:217], v[158:161], v[98:101]
	v_mfma_f32_16x16x32_bf16 v[86:89], v[206:209], v[166:169], v[86:89]
	v_mfma_f32_16x16x32_bf16 v[82:85], v[214:217], v[166:169], v[82:85]
	v_mfma_f32_16x16x32_bf16 v[70:73], v[206:209], v[198:201], v[70:73]
	v_mfma_f32_16x16x32_bf16 v[66:69], v[214:217], v[198:201], v[66:69]
	s_barrier
	s_setprio 0
	s_add_i32 s20, s77, s56
	v_lshl_add_u64 v[218:219], s[6:7], 0, v[176:177]
	s_mov_b32 m0, s20
	s_nop 0
	global_load_lds_dwordx4 v[218:219], off
	v_lshl_add_u64 v[220:221], s[6:7], 0, v[180:181]
	s_add_i32 m0, s20, 0x2000
	s_nop 0
	global_load_lds_dwordx4 v[220:221], off
	s_mov_b32 m0, s57
	v_lshl_add_u64 v[222:223], s[8:9], 0, v[172:173]
	ds_read_b128 v[146:149], v242 offset:16384
	ds_read_b128 v[150:153], v242 offset:17408
	ds_read_b128 v[154:157], v242 offset:18432
	ds_read_b128 v[158:161], v242 offset:19456
	ds_read_b128 v[162:165], v242 offset:20480
	ds_read_b128 v[166:169], v242 offset:21504
	ds_read_b128 v[194:197], v242 offset:22528
	ds_read_b128 v[198:201], v242 offset:23552
	global_load_lds_dwordx4 v[222:223], off
	v_lshl_add_u64 v[224:225], s[8:9], 0, v[178:179]
	s_mov_b32 m0, s68
	s_nop 0
	global_load_lds_dwordx4 v[224:225], off
	s_add_u32 s20, s6, 0xb0000
	s_addc_u32 s21, s7, 0
	s_add_i32 s50, s78, s56
	v_lshl_add_u64 v[246:247], s[20:21], 0, v[176:177]
	s_mov_b32 m0, s50
	s_nop 0
	global_load_lds_dwordx4 v[246:247], off
	v_lshl_add_u64 v[246:247], s[20:21], 0, v[180:181]
	s_add_i32 m0, s50, 0x2000
	s_nop 0
	global_load_lds_dwordx4 v[246:247], off
	s_waitcnt vmcnt(8)
	s_waitcnt lgkmcnt(0)
	s_setprio 1
	s_barrier
	v_mfma_f32_16x16x32_bf16 v[62:65], v[130:133], v[146:149], v[62:65]
	v_mfma_f32_16x16x32_bf16 v[58:61], v[138:141], v[146:149], v[58:61]
	v_mfma_f32_16x16x32_bf16 v[46:49], v[130:133], v[154:157], v[46:49]
	v_mfma_f32_16x16x32_bf16 v[42:45], v[138:141], v[154:157], v[42:45]
	v_mfma_f32_16x16x32_bf16 v[30:33], v[130:133], v[162:165], v[30:33]
	v_mfma_f32_16x16x32_bf16 v[26:29], v[138:141], v[162:165], v[26:29]
	v_mfma_f32_16x16x32_bf16 v[14:17], v[130:133], v[194:197], v[14:17]
	v_mfma_f32_16x16x32_bf16 v[10:13], v[138:141], v[194:197], v[10:13]
	v_mfma_f32_16x16x32_bf16 v[62:65], v[134:137], v[150:153], v[62:65]
	v_mfma_f32_16x16x32_bf16 v[58:61], v[142:145], v[150:153], v[58:61]
	v_mfma_f32_16x16x32_bf16 v[46:49], v[134:137], v[158:161], v[46:49]
	v_mfma_f32_16x16x32_bf16 v[42:45], v[142:145], v[158:161], v[42:45]
	v_mfma_f32_16x16x32_bf16 v[30:33], v[134:137], v[166:169], v[30:33]
	v_mfma_f32_16x16x32_bf16 v[26:29], v[142:145], v[166:169], v[26:29]
	v_mfma_f32_16x16x32_bf16 v[14:17], v[134:137], v[198:201], v[14:17]
	v_mfma_f32_16x16x32_bf16 v[10:13], v[142:145], v[198:201], v[10:13]
	v_mfma_f32_16x16x32_bf16 v[54:57], v[202:205], v[146:149], v[54:57]
	v_mfma_f32_16x16x32_bf16 v[50:53], v[210:213], v[146:149], v[50:53]
	v_mfma_f32_16x16x32_bf16 v[38:41], v[202:205], v[154:157], v[38:41]
	v_mfma_f32_16x16x32_bf16 v[34:37], v[210:213], v[154:157], v[34:37]
	v_mfma_f32_16x16x32_bf16 v[22:25], v[202:205], v[162:165], v[22:25]
	v_mfma_f32_16x16x32_bf16 v[18:21], v[210:213], v[162:165], v[18:21]
	v_mfma_f32_16x16x32_bf16 v[6:9], v[202:205], v[194:197], v[6:9]
	v_mfma_f32_16x16x32_bf16 v[2:5], v[210:213], v[194:197], v[2:5]
	v_mfma_f32_16x16x32_bf16 v[54:57], v[206:209], v[150:153], v[54:57]
	v_mfma_f32_16x16x32_bf16 v[50:53], v[214:217], v[150:153], v[50:53]
	v_mfma_f32_16x16x32_bf16 v[38:41], v[206:209], v[158:161], v[38:41]
	v_mfma_f32_16x16x32_bf16 v[34:37], v[214:217], v[158:161], v[34:37]
	v_mfma_f32_16x16x32_bf16 v[22:25], v[206:209], v[166:169], v[22:25]
	v_mfma_f32_16x16x32_bf16 v[18:21], v[214:217], v[166:169], v[18:21]
	v_mfma_f32_16x16x32_bf16 v[6:9], v[206:209], v[198:201], v[6:9]
	v_mfma_f32_16x16x32_bf16 v[2:5], v[214:217], v[198:201], v[2:5]
	s_barrier
	s_setprio 0
	s_add_i32 s20, 0, 0x18000
	v_add_u32_e32 v142, s20, v240
	ds_read_b128 v[130:133], v142
	ds_read_b128 v[134:137], v142 offset:1024
	ds_read_b128 v[138:141], v142 offset:2048
	ds_read_b128 v[142:145], v142 offset:3072
	s_add_u32 s8, s8, 0xb0000
	s_addc_u32 s9, s9, 0
	s_mov_b32 m0, s69
	v_lshl_add_u64 v[202:203], s[8:9], 0, v[172:173]
	ds_read_b128 v[146:149], v242 offset:32768
	ds_read_b128 v[150:153], v242 offset:33792
	ds_read_b128 v[154:157], v242 offset:34816
	ds_read_b128 v[158:161], v242 offset:35840
	ds_read_b128 v[162:165], v242 offset:36864
	ds_read_b128 v[166:169], v242 offset:37888
	ds_read_b128 v[194:197], v242 offset:38912
	ds_read_b128 v[198:201], v242 offset:39936
	global_load_lds_dwordx4 v[202:203], off
	v_lshl_add_u64 v[202:203], s[8:9], 0, v[178:179]
	s_mov_b32 m0, s70
	s_nop 0
	global_load_lds_dwordx4 v[202:203], off
	s_add_i32 s8, 0, 0x1c000
	v_add_u32_e32 v184, s8, v240
	ds_read_b128 v[202:205], v184
	ds_read_b128 v[206:209], v184 offset:1024
	ds_read_b128 v[210:213], v184 offset:2048
	ds_read_b128 v[214:217], v184 offset:3072
	s_waitcnt vmcnt(8)
	s_waitcnt lgkmcnt(0)
	s_setprio 1
	s_barrier
	v_mfma_f32_16x16x32_bf16 v[126:129], v[130:133], v[146:149], v[126:129]
	v_mfma_f32_16x16x32_bf16 v[122:125], v[138:141], v[146:149], v[122:125]
	v_mfma_f32_16x16x32_bf16 v[110:113], v[130:133], v[154:157], v[110:113]
	v_mfma_f32_16x16x32_bf16 v[106:109], v[138:141], v[154:157], v[106:109]
	v_mfma_f32_16x16x32_bf16 v[94:97], v[130:133], v[162:165], v[94:97]
	v_mfma_f32_16x16x32_bf16 v[90:93], v[138:141], v[162:165], v[90:93]
	v_mfma_f32_16x16x32_bf16 v[78:81], v[130:133], v[194:197], v[78:81]
	v_mfma_f32_16x16x32_bf16 v[74:77], v[138:141], v[194:197], v[74:77]
	v_mfma_f32_16x16x32_bf16 v[126:129], v[134:137], v[150:153], v[126:129]
	v_mfma_f32_16x16x32_bf16 v[122:125], v[142:145], v[150:153], v[122:125]
	v_mfma_f32_16x16x32_bf16 v[110:113], v[134:137], v[158:161], v[110:113]
	v_mfma_f32_16x16x32_bf16 v[106:109], v[142:145], v[158:161], v[106:109]
	v_mfma_f32_16x16x32_bf16 v[94:97], v[134:137], v[166:169], v[94:97]
	v_mfma_f32_16x16x32_bf16 v[90:93], v[142:145], v[166:169], v[90:93]
	v_mfma_f32_16x16x32_bf16 v[78:81], v[134:137], v[198:201], v[78:81]
	v_mfma_f32_16x16x32_bf16 v[74:77], v[142:145], v[198:201], v[74:77]
	v_mfma_f32_16x16x32_bf16 v[118:121], v[202:205], v[146:149], v[118:121]
	v_mfma_f32_16x16x32_bf16 v[114:117], v[210:213], v[146:149], v[114:117]
	v_mfma_f32_16x16x32_bf16 v[102:105], v[202:205], v[154:157], v[102:105]
	v_mfma_f32_16x16x32_bf16 v[98:101], v[210:213], v[154:157], v[98:101]
	v_mfma_f32_16x16x32_bf16 v[86:89], v[202:205], v[162:165], v[86:89]
	v_mfma_f32_16x16x32_bf16 v[82:85], v[210:213], v[162:165], v[82:85]
	v_mfma_f32_16x16x32_bf16 v[70:73], v[202:205], v[194:197], v[70:73]
	v_mfma_f32_16x16x32_bf16 v[66:69], v[210:213], v[194:197], v[66:69]
	v_mfma_f32_16x16x32_bf16 v[118:121], v[206:209], v[150:153], v[118:121]
	v_mfma_f32_16x16x32_bf16 v[114:117], v[214:217], v[150:153], v[114:117]
	v_mfma_f32_16x16x32_bf16 v[102:105], v[206:209], v[158:161], v[102:105]
	v_mfma_f32_16x16x32_bf16 v[98:101], v[214:217], v[158:161], v[98:101]
	v_mfma_f32_16x16x32_bf16 v[86:89], v[206:209], v[166:169], v[86:89]
	v_mfma_f32_16x16x32_bf16 v[82:85], v[214:217], v[166:169], v[82:85]
	v_mfma_f32_16x16x32_bf16 v[70:73], v[206:209], v[198:201], v[70:73]
	v_mfma_f32_16x16x32_bf16 v[66:69], v[214:217], v[198:201], v[66:69]
	s_barrier
	s_setprio 0
	s_add_i32 s9, s20, s56
	v_lshl_add_u64 v[218:219], v[218:219], 0, s[16:17]
	s_mov_b32 m0, s9
	s_nop 0
	global_load_lds_dwordx4 v[218:219], off
	v_lshl_add_u64 v[218:219], v[220:221], 0, s[16:17]
	s_add_i32 m0, s9, 0x2000
	s_nop 0
	global_load_lds_dwordx4 v[218:219], off
	s_mov_b32 m0, s74
	v_lshl_add_u64 v[218:219], v[222:223], 0, s[16:17]
	ds_read_b128 v[146:149], v242 offset:49152
	ds_read_b128 v[150:153], v242 offset:50176
	ds_read_b128 v[154:157], v242 offset:51200
	ds_read_b128 v[158:161], v242 offset:52224
	ds_read_b128 v[162:165], v242 offset:53248
	ds_read_b128 v[166:169], v242 offset:54272
	ds_read_b128 v[194:197], v242 offset:55296
	ds_read_b128 v[198:201], v242 offset:56320
	global_load_lds_dwordx4 v[218:219], off
	v_lshl_add_u64 v[218:219], v[224:225], 0, s[16:17]
	s_mov_b32 m0, s75
	s_nop 0
	global_load_lds_dwordx4 v[218:219], off
	s_add_u32 s6, s6, 0xb0080
	s_addc_u32 s7, s7, 0
	s_add_i32 s8, s8, s56
	v_lshl_add_u64 v[248:249], s[6:7], 0, v[176:177]
	s_mov_b32 m0, s8
	s_nop 0
	global_load_lds_dwordx4 v[248:249], off
	v_lshl_add_u64 v[248:249], s[6:7], 0, v[180:181]
	s_add_i32 m0, s8, 0x2000
	s_nop 0
	global_load_lds_dwordx4 v[248:249], off
	s_waitcnt vmcnt(8)
	s_waitcnt lgkmcnt(0)
	s_setprio 1
	s_barrier
	v_mfma_f32_16x16x32_bf16 v[62:65], v[130:133], v[146:149], v[62:65]
	v_mfma_f32_16x16x32_bf16 v[58:61], v[138:141], v[146:149], v[58:61]
	v_mfma_f32_16x16x32_bf16 v[46:49], v[130:133], v[154:157], v[46:49]
	v_mfma_f32_16x16x32_bf16 v[42:45], v[138:141], v[154:157], v[42:45]
	v_mfma_f32_16x16x32_bf16 v[30:33], v[130:133], v[162:165], v[30:33]
	v_mfma_f32_16x16x32_bf16 v[26:29], v[138:141], v[162:165], v[26:29]
	v_mfma_f32_16x16x32_bf16 v[14:17], v[130:133], v[194:197], v[14:17]
	v_mfma_f32_16x16x32_bf16 v[10:13], v[138:141], v[194:197], v[10:13]
	v_mfma_f32_16x16x32_bf16 v[62:65], v[134:137], v[150:153], v[62:65]
	v_mfma_f32_16x16x32_bf16 v[58:61], v[142:145], v[150:153], v[58:61]
	v_mfma_f32_16x16x32_bf16 v[46:49], v[134:137], v[158:161], v[46:49]
	v_mfma_f32_16x16x32_bf16 v[42:45], v[142:145], v[158:161], v[42:45]
	v_mfma_f32_16x16x32_bf16 v[30:33], v[134:137], v[166:169], v[30:33]
	v_mfma_f32_16x16x32_bf16 v[26:29], v[142:145], v[166:169], v[26:29]
	v_mfma_f32_16x16x32_bf16 v[14:17], v[134:137], v[198:201], v[14:17]
	v_mfma_f32_16x16x32_bf16 v[10:13], v[142:145], v[198:201], v[10:13]
	v_mfma_f32_16x16x32_bf16 v[54:57], v[202:205], v[146:149], v[54:57]
	v_mfma_f32_16x16x32_bf16 v[50:53], v[210:213], v[146:149], v[50:53]
	v_mfma_f32_16x16x32_bf16 v[38:41], v[202:205], v[154:157], v[38:41]
	v_mfma_f32_16x16x32_bf16 v[34:37], v[210:213], v[154:157], v[34:37]
	v_mfma_f32_16x16x32_bf16 v[22:25], v[202:205], v[162:165], v[22:25]
	v_mfma_f32_16x16x32_bf16 v[18:21], v[210:213], v[162:165], v[18:21]
	v_mfma_f32_16x16x32_bf16 v[6:9], v[202:205], v[194:197], v[6:9]
	v_mfma_f32_16x16x32_bf16 v[2:5], v[210:213], v[194:197], v[2:5]
	v_mfma_f32_16x16x32_bf16 v[54:57], v[206:209], v[150:153], v[54:57]
	v_mfma_f32_16x16x32_bf16 v[50:53], v[214:217], v[150:153], v[50:53]
	v_mfma_f32_16x16x32_bf16 v[38:41], v[206:209], v[158:161], v[38:41]
	v_mfma_f32_16x16x32_bf16 v[34:37], v[214:217], v[158:161], v[34:37]
	v_mfma_f32_16x16x32_bf16 v[22:25], v[206:209], v[166:169], v[22:25]
	v_mfma_f32_16x16x32_bf16 v[18:21], v[214:217], v[166:169], v[18:21]
	v_mfma_f32_16x16x32_bf16 v[6:9], v[206:209], v[198:201], v[6:9]
	v_mfma_f32_16x16x32_bf16 v[2:5], v[214:217], v[198:201], v[2:5]
	s_barrier
	s_setprio 0
	s_add_i32 s49, s49, 2
	s_add_u32 s0, s0, 0x100
	s_addc_u32 s1, s1, 0
	s_add_u32 s10, s10, 0x100
	s_addc_u32 s11, s11, 0
	s_cmp_gt_u32 s49, 41
	s_cbranch_scc0 .LBB0_822
	s_min_i32 s0, s48, 0x80
	s_ashr_i32 s0, s0, 3
	s_mul_hi_i32 s1, s0, 0x9000
	s_mul_i32 s0, s0, 0x9000
	s_add_u32 s6, s58, s0
	s_addc_u32 s7, s59, s1
	s_lshl_b32 s50, s34, 8
	s_ashr_i32 s51, s50, 31
	s_lshl_b64 s[0:1], s[50:51], 2
	s_add_u32 s0, s6, s0
	s_addc_u32 s1, s7, s1
	v_lshlrev_b32_e32 v184, 2, v182
	v_lshl_add_u64 v[130:131], s[0:1], 0, v[184:185]
	s_mov_b64 s[0:1], 0x2000
	v_lshl_add_u64 v[132:133], v[130:131], 0, s[0:1]
	s_movk_i32 s0, 0x2000
	v_add_co_u32_e32 v134, vcc, s0, v130
	s_mov_b64 s[0:1], 0x2200
	s_nop 0
	v_addc_co_u32_e32 v135, vcc, 0, v131, vcc
	global_load_dwordx4 v[194:197], v[134:135], off
	global_load_dwordx4 v[220:223], v[132:133], off offset:16
	v_lshl_add_u64 v[132:133], v[130:131], 0, s[0:1]
	s_mov_b64 s[0:1], 0x4000
	global_load_dwordx4 v[198:201], v[134:135], off offset:512
	global_load_dwordx4 v[224:227], v[132:133], off offset:16
	v_lshl_add_u64 v[132:133], v[130:131], 0, s[0:1]
	s_movk_i32 s0, 0x4000
	v_add_co_u32_e32 v134, vcc, s0, v130
	s_mov_b64 s[0:1], 0x4200
	v_lshl_add_u32 v212, s48, 8, v239
	v_addc_co_u32_e32 v135, vcc, 0, v131, vcc
	v_lshl_add_u64 v[130:131], v[130:131], 0, s[0:1]
	global_load_dwordx4 v[154:157], v[134:135], off
	global_load_dwordx4 v[162:165], v[132:133], off offset:16
	global_load_dwordx4 v[158:161], v[134:135], off offset:512
	global_load_dwordx4 v[166:169], v[130:131], off offset:16
	v_add_u32_e32 v130, 0xffff8000, v212
	v_ashrrev_i32_e32 v213, 31, v212
	v_cmp_gt_i32_e64 s[6:7], s76, v212
	v_mov_b32_e32 v134, s72
	v_mov_b32_e32 v135, s29
	v_cndmask_b32_e64 v131, 0, v213, s[6:7]
	v_cndmask_b32_e64 v130, v130, v212, s[6:7]
	v_mov_b32_e32 v136, s71
	v_mov_b32_e32 v137, s28
	v_cndmask_b32_e64 v133, v134, v135, s[6:7]
	v_cndmask_b32_e64 v132, v136, v137, s[6:7]
	v_lshlrev_b64 v[130:131], 11, v[130:131]
	v_lshl_add_u64 v[130:131], v[132:133], 0, v[130:131]
	s_lshl_b64 s[0:1], s[50:51], 1
	v_lshl_add_u64 v[130:131], v[130:131], 0, s[0:1]
	v_lshlrev_b32_e32 v184, 1, v182
	v_lshl_add_u64 v[130:131], v[130:131], 0, v[184:185]
	v_or_b32_e32 v218, 16, v212
	global_load_dwordx4 v[246:249], v[130:131], off
	global_load_dwordx4 v[250:253], v[130:131], off offset:256
	v_add_u32_e32 v130, 0xffff8010, v212
	v_ashrrev_i32_e32 v219, 31, v218
	v_cmp_gt_i32_e64 s[8:9], s76, v218
	v_or_b32_e32 v216, 32, v212
	v_ashrrev_i32_e32 v217, 31, v216
	v_cndmask_b32_e64 v131, 0, v219, s[8:9]
	v_cndmask_b32_e64 v130, v130, v218, s[8:9]
	v_cndmask_b32_e64 v133, v134, v135, s[8:9]
	v_cndmask_b32_e64 v132, v136, v137, s[8:9]
	v_lshlrev_b64 v[130:131], 11, v[130:131]
	v_lshl_add_u64 v[130:131], v[132:133], 0, v[130:131]
	v_lshl_add_u64 v[130:131], v[130:131], 0, s[0:1]
	v_lshl_add_u64 v[130:131], v[130:131], 0, v[184:185]
	global_load_dwordx4 v[150:153], v[130:131], off
	global_load_dwordx4 v[146:149], v[130:131], off offset:256
	v_add_u32_e32 v130, 0xffff8020, v212
	v_cmp_gt_i32_e64 s[10:11], s76, v216
	v_or_b32_e32 v214, 48, v212
	v_ashrrev_i32_e32 v215, 31, v214
	v_cndmask_b32_e64 v131, 0, v217, s[10:11]
	v_cndmask_b32_e64 v130, v130, v216, s[10:11]
	v_cndmask_b32_e64 v133, v134, v135, s[10:11]
	v_cndmask_b32_e64 v132, v136, v137, s[10:11]
	v_lshlrev_b64 v[130:131], 11, v[130:131]
	v_lshl_add_u64 v[130:131], v[132:133], 0, v[130:131]
	v_lshl_add_u64 v[130:131], v[130:131], 0, s[0:1]
	v_lshl_add_u64 v[130:131], v[130:131], 0, v[184:185]
	global_load_dwordx4 v[142:145], v[130:131], off
	global_load_dwordx4 v[138:141], v[130:131], off offset:256
	v_add_u32_e32 v130, 0xffff8030, v212
	v_cmp_gt_i32_e32 vcc, s76, v214
	s_waitcnt vmcnt(0)
	v_pk_mul_f32 v[210:211], v[194:195], 0.5 op_sel_hi:[1,0]
	v_cndmask_b32_e32 v131, 0, v215, vcc
	v_cndmask_b32_e32 v130, v130, v214, vcc
	v_cndmask_b32_e32 v133, v134, v135, vcc
	v_cndmask_b32_e32 v132, v136, v137, vcc
	v_lshlrev_b64 v[130:131], 11, v[130:131]
	v_lshl_add_u64 v[130:131], v[132:133], 0, v[130:131]
	v_lshl_add_u64 v[130:131], v[130:131], 0, s[0:1]
	v_lshl_add_u64 v[130:131], v[130:131], 0, v[184:185]
	global_load_dwordx4 v[134:137], v[130:131], off
	s_nop 0
	global_load_dwordx4 v[130:133], v[130:131], off offset:256
	v_pk_mul_f32 v[202:203], v[220:221], 0.5 op_sel_hi:[1,0]
	v_pk_mul_f32 v[208:209], v[198:199], 0.5 op_sel_hi:[1,0]
	v_pk_mul_f32 v[206:207], v[196:197], 0.5 op_sel_hi:[1,0]
	v_pk_mul_f32 v[204:205], v[200:201], 0.5 op_sel_hi:[1,0]
	v_pk_mul_f32 v[198:199], v[222:223], 0.5 op_sel_hi:[1,0]
	v_pk_mul_f32 v[200:201], v[224:225], 0.5 op_sel_hi:[1,0]
	v_pk_mul_f32 v[196:197], v[226:227], 0.5 op_sel_hi:[1,0]
	v_mov_b32_e32 v195, s51
	v_or_b32_e32 v194, s50, v182
	v_lshlrev_b32_e32 v220, 16, v246
	v_and_b32_e32 v221, 0xffff0000, v246
	v_pk_fma_f32 v[220:221], v[126:127], v[210:211], v[220:221]
	v_lshlrev_b32_e32 v126, 16, v250
	v_and_b32_e32 v127, 0xffff0000, v250
	v_pk_fma_f32 v[118:119], v[118:119], v[208:209], v[126:127]
	v_lshlrev_b32_e32 v126, 16, v247
	v_and_b32_e32 v127, 0xffff0000, v247
	v_pk_fma_f32 v[222:223], v[128:129], v[206:207], v[126:127]
	v_lshlrev_b32_e32 v126, 16, v251
	v_and_b32_e32 v127, 0xffff0000, v251
	v_pk_fma_f32 v[120:121], v[120:121], v[204:205], v[126:127]
	v_lshlrev_b32_e32 v126, 16, v248
	v_and_b32_e32 v127, 0xffff0000, v248
	v_pk_fma_f32 v[224:225], v[122:123], v[202:203], v[126:127]
	v_lshlrev_b32_e32 v122, 16, v252
	v_and_b32_e32 v123, 0xffff0000, v252
	v_pk_fma_f32 v[114:115], v[114:115], v[200:201], v[122:123]
	v_lshlrev_b32_e32 v122, 16, v249
	v_and_b32_e32 v123, 0xffff0000, v249
	v_pk_fma_f32 v[226:227], v[124:125], v[198:199], v[122:123]
	v_lshlrev_b32_e32 v122, 16, v253
	v_and_b32_e32 v123, 0xffff0000, v253
	v_pk_fma_f32 v[116:117], v[116:117], v[196:197], v[122:123]
	v_lshlrev_b64 v[122:123], 10, v[212:213]
	v_lshl_add_u64 v[228:229], v[122:123], 0, v[194:195]
	s_and_saveexec_b64 s[0:1], s[6:7]
	s_cbranch_execz .LBB0_825
	v_lshl_add_u64 v[126:127], v[228:229], 1, s[28:29]
	v_cvt_pk_bf16_f32 v122, v220, v221
	v_cvt_pk_bf16_f32 v123, v222, v223
	v_cvt_pk_bf16_f32 v124, v224, v225
	v_cvt_pk_bf16_f32 v125, v226, v227
	global_store_dwordx4 v[126:127], v[122:125], off nt
	s_nop 1
	v_cvt_pk_bf16_f32 v122, v118, v119
	v_cvt_pk_bf16_f32 v123, v120, v121
	v_cvt_pk_bf16_f32 v124, v114, v115
	v_cvt_pk_bf16_f32 v125, v116, v117
	global_store_dwordx4 v[126:127], v[122:125], off offset:256 nt

.LBB0_861:
	s_lshl_b32 s5, s5, 5
	s_and_b32 s5, s5, 0x60
	s_lshl_b32 s10, s1, 13
	s_lshl_b32 s11, s5, 7
	s_add_u32 s51, s30, 0xe100000
	s_addc_u32 s53, s31, 0
	s_mov_b64 s[8:9], 0x80
	s_add_u32 s6, s14, 0xb0080
	v_lshl_add_u64 v[2:3], v[2:3], 0, s[8:9]
	s_addc_u32 s7, s15, 0
	s_add_i32 m0, s40, 0x18000
	v_lshl_add_u64 v[4:5], v[4:5], 0, s[8:9]
	s_waitcnt vmcnt(0)
	s_barrier
	global_load_lds_dwordx4 v[2:3], off
	s_add_i32 m0, s40, 0x1a000
	s_add_i32 s54, s40, 0x8000
	v_lshl_add_u64 v[6:7], v[6:7], 0, s[8:9]
	global_load_lds_dwordx4 v[4:5], off
	s_mov_b32 m0, s54
	s_add_i32 s55, s40, 0xa000
	v_lshl_add_u64 v[8:9], v[8:9], 0, s[8:9]
	global_load_lds_dwordx4 v[6:7], off
	s_mov_b32 m0, s55
	v_lshl_add_u64 v[10:11], s[6:7], 0, v[176:177]
	global_load_lds_dwordx4 v[8:9], off
	s_add_i32 m0, s40, 0x1c000
	v_lshl_add_u64 v[12:13], s[6:7], 0, v[180:181]
	global_load_lds_dwordx4 v[10:11], off
	s_add_i32 m0, s40, 0x1e000
	v_lshlrev_b32_e32 v2, 1, v171
	global_load_lds_dwordx4 v[12:13], off
	v_or_b32_e32 v3, v2, v238
	v_lshlrev_b32_e32 v4, 2, v175
	v_lshl_or_b32 v2, v175, 6, v2
	v_and_b32_e32 v4, 32, v4
	v_bitop3_b32 v141, s11, v3, v237 bitop3:0xf6
	s_waitcnt vmcnt(6)
	v_add_u16_e32 v3, v235, v236
	s_add_i32 s70, 0, 0x10000
	v_bitop3_b32 v4, v2, s10, v4 bitop3:0xde
	v_or_b32_e32 v2, s5, v171
	v_mov_b32_e32 v131, 0
	v_lshrrev_b16_e32 v3, 1, v3
	v_add_u32_e32 v142, s70, v141
	s_add_i32 s56, 0, 0x14000
	s_add_i32 s70, s70, s35
	v_lshl_or_b32 v140, s1, 6, v175
	s_sext_i32_i8 s76, s0
	s_sext_i32_i8 s77, s4
	v_add_lshl_u32 v132, v233, v3, 1
	v_mov_b32_e32 v133, v131
	v_add_lshl_u32 v134, v234, v3, 1
	v_mov_b32_e32 v135, v131
	v_mov_b64_e32 v[136:137], 0x80
	v_mov_b64_e32 v[138:139], 0x7f
	v_add_u32_e32 v143, 0, v4
	v_add_u32_e32 v144, s56, v141
	v_lshlrev_b32_e32 v130, 1, v2
	s_mov_b64 s[10:11], 0x40000
	s_mov_b32 s57, 0x40000
	s_add_i32 s68, s40, 0xc000
	s_add_i32 s69, s40, 0xe000
	s_add_i32 s71, s70, 0x2000
	s_barrier

.LBB0_868:
	s_add_u32 s12, s12, 0xb0080
	s_addc_u32 s13, s13, 0
	s_add_u32 s78, s14, 0x100
	s_addc_u32 s79, s15, 0
	s_mov_b32 s87, -2
	ds_read_b128 v[146:149], v142
	ds_read_b128 v[150:153], v142 offset:1024
	ds_read_b128 v[154:157], v142 offset:2048
	ds_read_b128 v[158:161], v142 offset:3072
	s_add_u32 s14, s12, 0xfff50080
	s_addc_u32 s15, s13, -1
	s_cmp_eq_u32 s87, 18
	s_cselect_b32 s17, s1, s15
	s_cselect_b32 s16, s0, s14
	s_cselect_b32 s15, s7, s79
	s_cselect_b32 s14, s6, s78
	s_mov_b32 m0, s68
	v_lshl_add_u64 v[208:209], s[12:13], 0, v[132:133]
	ds_read_b128 v[162:165], v143
	ds_read_b128 v[166:169], v143 offset:1024
	ds_read_b128 v[184:187], v143 offset:2048
	ds_read_b128 v[188:191], v143 offset:3072
	ds_read_b128 v[192:195], v143 offset:4096
	ds_read_b128 v[196:199], v143 offset:5120
	ds_read_b128 v[200:203], v143 offset:6144
	ds_read_b128 v[204:207], v143 offset:7168
	global_load_lds_dwordx4 v[208:209], off
	v_lshl_add_u64 v[208:209], s[12:13], 0, v[134:135]
	s_mov_b32 m0, s69
	s_nop 0
	global_load_lds_dwordx4 v[208:209], off
	ds_read_b128 v[208:211], v144
	ds_read_b128 v[212:215], v144 offset:1024
	ds_read_b128 v[216:219], v144 offset:2048
	ds_read_b128 v[220:223], v144 offset:3072
	s_waitcnt vmcnt(8)
	s_waitcnt lgkmcnt(0)
	s_setprio 1
	s_barrier
	v_mfma_f32_16x16x32_bf16 v[126:129], v[146:149], v[162:165], 0
	v_mfma_f32_16x16x32_bf16 v[122:125], v[154:157], v[162:165], 0
	v_mfma_f32_16x16x32_bf16 v[118:121], v[146:149], v[184:187], 0
	v_mfma_f32_16x16x32_bf16 v[114:117], v[154:157], v[184:187], 0
	v_mfma_f32_16x16x32_bf16 v[102:105], v[146:149], v[192:195], 0
	v_mfma_f32_16x16x32_bf16 v[98:101], v[154:157], v[192:195], 0
	v_mfma_f32_16x16x32_bf16 v[86:89], v[146:149], v[200:203], 0
	v_mfma_f32_16x16x32_bf16 v[82:85], v[154:157], v[200:203], 0
	v_mfma_f32_16x16x32_bf16 v[126:129], v[150:153], v[166:169], v[126:129]
	v_mfma_f32_16x16x32_bf16 v[122:125], v[158:161], v[166:169], v[122:125]
	v_mfma_f32_16x16x32_bf16 v[118:121], v[150:153], v[188:191], v[118:121]
	v_mfma_f32_16x16x32_bf16 v[114:117], v[158:161], v[188:191], v[114:117]
	v_mfma_f32_16x16x32_bf16 v[102:105], v[150:153], v[196:199], v[102:105]
	v_mfma_f32_16x16x32_bf16 v[98:101], v[158:161], v[196:199], v[98:101]
	v_mfma_f32_16x16x32_bf16 v[86:89], v[150:153], v[204:207], v[86:89]
	v_mfma_f32_16x16x32_bf16 v[82:85], v[158:161], v[204:207], v[82:85]
	v_mfma_f32_16x16x32_bf16 v[110:113], v[208:211], v[162:165], 0
	v_mfma_f32_16x16x32_bf16 v[106:109], v[216:219], v[162:165], 0
	v_mfma_f32_16x16x32_bf16 v[94:97], v[208:211], v[184:187], 0
	v_mfma_f32_16x16x32_bf16 v[90:93], v[216:219], v[184:187], 0
	v_mfma_f32_16x16x32_bf16 v[78:81], v[208:211], v[192:195], 0
	v_mfma_f32_16x16x32_bf16 v[74:77], v[216:219], v[192:195], 0
	v_mfma_f32_16x16x32_bf16 v[70:73], v[208:211], v[200:203], 0
	v_mfma_f32_16x16x32_bf16 v[66:69], v[216:219], v[200:203], 0
	v_mfma_f32_16x16x32_bf16 v[110:113], v[212:215], v[166:169], v[110:113]
	v_mfma_f32_16x16x32_bf16 v[106:109], v[220:223], v[166:169], v[106:109]
	v_mfma_f32_16x16x32_bf16 v[94:97], v[212:215], v[188:191], v[94:97]
	v_mfma_f32_16x16x32_bf16 v[90:93], v[220:223], v[188:191], v[90:93]
	v_mfma_f32_16x16x32_bf16 v[78:81], v[212:215], v[196:199], v[78:81]
	v_mfma_f32_16x16x32_bf16 v[74:77], v[220:223], v[196:199], v[74:77]
	v_mfma_f32_16x16x32_bf16 v[70:73], v[212:215], v[204:207], v[70:73]
	v_mfma_f32_16x16x32_bf16 v[66:69], v[220:223], v[204:207], v[66:69]
	s_barrier
	s_setprio 0
	s_mov_b32 m0, s70
	v_lshl_add_u64 v[224:225], s[14:15], 0, v[176:177]
	global_load_lds_dwordx4 v[224:225], off
	v_lshl_add_u64 v[226:227], s[14:15], 0, v[180:181]
	s_mov_b32 m0, s71
	s_nop 0
	global_load_lds_dwordx4 v[226:227], off
	s_mov_b32 m0, s40
	v_lshl_add_u64 v[228:229], s[16:17], 0, v[172:173]
	ds_read_b128 v[162:165], v143 offset:16384
	ds_read_b128 v[166:169], v143 offset:17408
	ds_read_b128 v[184:187], v143 offset:18432
	ds_read_b128 v[188:191], v143 offset:19456
	ds_read_b128 v[192:195], v143 offset:20480
	ds_read_b128 v[196:199], v143 offset:21504
	ds_read_b128 v[200:203], v143 offset:22528
	ds_read_b128 v[204:207], v143 offset:23552
	global_load_lds_dwordx4 v[228:229], off
	v_lshl_add_u64 v[234:235], s[16:17], 0, v[178:179]
	s_mov_b32 m0, s41
	s_nop 0
	global_load_lds_dwordx4 v[234:235], off
	s_add_u32 s20, s14, 0xb0000
	s_addc_u32 s21, s15, 0
	s_add_i32 s60, s56, s35
	v_lshl_add_u64 v[246:247], s[20:21], 0, v[176:177]
	s_mov_b32 m0, s60
	s_nop 0
	global_load_lds_dwordx4 v[246:247], off
	v_lshl_add_u64 v[246:247], s[20:21], 0, v[180:181]
	s_add_i32 m0, s60, 0x2000
	s_nop 0
	global_load_lds_dwordx4 v[246:247], off
	s_waitcnt vmcnt(8)
	s_waitcnt lgkmcnt(0)
	s_setprio 1
	s_barrier
	v_mfma_f32_16x16x32_bf16 v[62:65], v[146:149], v[162:165], 0
	v_mfma_f32_16x16x32_bf16 v[58:61], v[154:157], v[162:165], 0
	v_mfma_f32_16x16x32_bf16 v[54:57], v[146:149], v[184:187], 0
	v_mfma_f32_16x16x32_bf16 v[50:53], v[154:157], v[184:187], 0
	v_mfma_f32_16x16x32_bf16 v[38:41], v[146:149], v[192:195], 0
	v_mfma_f32_16x16x32_bf16 v[34:37], v[154:157], v[192:195], 0
	v_mfma_f32_16x16x32_bf16 v[22:25], v[146:149], v[200:203], 0
	v_mfma_f32_16x16x32_bf16 v[18:21], v[154:157], v[200:203], 0
	v_mfma_f32_16x16x32_bf16 v[62:65], v[150:153], v[166:169], v[62:65]
	v_mfma_f32_16x16x32_bf16 v[58:61], v[158:161], v[166:169], v[58:61]
	v_mfma_f32_16x16x32_bf16 v[54:57], v[150:153], v[188:191], v[54:57]
	v_mfma_f32_16x16x32_bf16 v[50:53], v[158:161], v[188:191], v[50:53]
	v_mfma_f32_16x16x32_bf16 v[38:41], v[150:153], v[196:199], v[38:41]
	v_mfma_f32_16x16x32_bf16 v[34:37], v[158:161], v[196:199], v[34:37]
	v_mfma_f32_16x16x32_bf16 v[22:25], v[150:153], v[204:207], v[22:25]
	v_mfma_f32_16x16x32_bf16 v[18:21], v[158:161], v[204:207], v[18:21]
	v_mfma_f32_16x16x32_bf16 v[46:49], v[208:211], v[162:165], 0
	v_mfma_f32_16x16x32_bf16 v[42:45], v[216:219], v[162:165], 0
	v_mfma_f32_16x16x32_bf16 v[30:33], v[208:211], v[184:187], 0
	v_mfma_f32_16x16x32_bf16 v[26:29], v[216:219], v[184:187], 0
	v_mfma_f32_16x16x32_bf16 v[14:17], v[208:211], v[192:195], 0
	v_mfma_f32_16x16x32_bf16 v[10:13], v[216:219], v[192:195], 0
	v_mfma_f32_16x16x32_bf16 v[6:9], v[208:211], v[200:203], 0
	v_mfma_f32_16x16x32_bf16 v[2:5], v[216:219], v[200:203], 0
	v_mfma_f32_16x16x32_bf16 v[46:49], v[212:215], v[166:169], v[46:49]
	v_mfma_f32_16x16x32_bf16 v[42:45], v[220:223], v[166:169], v[42:45]
	v_mfma_f32_16x16x32_bf16 v[30:33], v[212:215], v[188:191], v[30:33]
	v_mfma_f32_16x16x32_bf16 v[26:29], v[220:223], v[188:191], v[26:29]
	v_mfma_f32_16x16x32_bf16 v[14:17], v[212:215], v[196:199], v[14:17]
	v_mfma_f32_16x16x32_bf16 v[10:13], v[220:223], v[196:199], v[10:13]
	v_mfma_f32_16x16x32_bf16 v[6:9], v[212:215], v[204:207], v[6:9]
	v_mfma_f32_16x16x32_bf16 v[2:5], v[220:223], v[204:207], v[2:5]
	s_barrier
	s_setprio 0
	s_add_i32 s20, 0, 0x18000
	v_add_u32_e32 v145, s20, v141
	ds_read_b128 v[146:149], v145
	ds_read_b128 v[150:153], v145 offset:1024
	ds_read_b128 v[154:157], v145 offset:2048
	ds_read_b128 v[158:161], v145 offset:3072
	s_add_u32 s16, s16, 0xb0000
	s_addc_u32 s17, s17, 0
	s_mov_b32 m0, s48
	v_lshl_add_u64 v[208:209], s[16:17], 0, v[172:173]
	ds_read_b128 v[162:165], v143 offset:32768
	ds_read_b128 v[166:169], v143 offset:33792
	ds_read_b128 v[184:187], v143 offset:34816
	ds_read_b128 v[188:191], v143 offset:35840
	ds_read_b128 v[192:195], v143 offset:36864
	ds_read_b128 v[196:199], v143 offset:37888
	ds_read_b128 v[200:203], v143 offset:38912
	ds_read_b128 v[204:207], v143 offset:39936
	global_load_lds_dwordx4 v[208:209], off
	v_lshl_add_u64 v[208:209], s[16:17], 0, v[178:179]
	s_mov_b32 m0, s49
	s_nop 0
	global_load_lds_dwordx4 v[208:209], off
	s_add_i32 s16, 0, 0x1c000
	v_add_u32_e32 v145, s16, v141
	ds_read_b128 v[208:211], v145
	ds_read_b128 v[212:215], v145 offset:1024
	ds_read_b128 v[216:219], v145 offset:2048
	ds_read_b128 v[220:223], v145 offset:3072
	s_waitcnt vmcnt(8)
	s_waitcnt lgkmcnt(0)
	s_setprio 1
	s_barrier
	v_mfma_f32_16x16x32_bf16 v[126:129], v[146:149], v[162:165], v[126:129]
	v_mfma_f32_16x16x32_bf16 v[122:125], v[154:157], v[162:165], v[122:125]
	v_mfma_f32_16x16x32_bf16 v[118:121], v[146:149], v[184:187], v[118:121]
	v_mfma_f32_16x16x32_bf16 v[114:117], v[154:157], v[184:187], v[114:117]
	v_mfma_f32_16x16x32_bf16 v[102:105], v[146:149], v[192:195], v[102:105]
	v_mfma_f32_16x16x32_bf16 v[98:101], v[154:157], v[192:195], v[98:101]
	v_mfma_f32_16x16x32_bf16 v[86:89], v[146:149], v[200:203], v[86:89]
	v_mfma_f32_16x16x32_bf16 v[82:85], v[154:157], v[200:203], v[82:85]
	v_mfma_f32_16x16x32_bf16 v[126:129], v[150:153], v[166:169], v[126:129]
	v_mfma_f32_16x16x32_bf16 v[122:125], v[158:161], v[166:169], v[122:125]
	v_mfma_f32_16x16x32_bf16 v[118:121], v[150:153], v[188:191], v[118:121]
	v_mfma_f32_16x16x32_bf16 v[114:117], v[158:161], v[188:191], v[114:117]
	v_mfma_f32_16x16x32_bf16 v[102:105], v[150:153], v[196:199], v[102:105]
	v_mfma_f32_16x16x32_bf16 v[98:101], v[158:161], v[196:199], v[98:101]
	v_mfma_f32_16x16x32_bf16 v[86:89], v[150:153], v[204:207], v[86:89]
	v_mfma_f32_16x16x32_bf16 v[82:85], v[158:161], v[204:207], v[82:85]
	v_mfma_f32_16x16x32_bf16 v[110:113], v[208:211], v[162:165], v[110:113]
	v_mfma_f32_16x16x32_bf16 v[106:109], v[216:219], v[162:165], v[106:109]
	v_mfma_f32_16x16x32_bf16 v[94:97], v[208:211], v[184:187], v[94:97]
	v_mfma_f32_16x16x32_bf16 v[90:93], v[216:219], v[184:187], v[90:93]
	v_mfma_f32_16x16x32_bf16 v[78:81], v[208:211], v[192:195], v[78:81]
	v_mfma_f32_16x16x32_bf16 v[74:77], v[216:219], v[192:195], v[74:77]
	v_mfma_f32_16x16x32_bf16 v[70:73], v[208:211], v[200:203], v[70:73]
	v_mfma_f32_16x16x32_bf16 v[66:69], v[216:219], v[200:203], v[66:69]
	v_mfma_f32_16x16x32_bf16 v[110:113], v[212:215], v[166:169], v[110:113]
	v_mfma_f32_16x16x32_bf16 v[106:109], v[220:223], v[166:169], v[106:109]
	v_mfma_f32_16x16x32_bf16 v[94:97], v[212:215], v[188:191], v[94:97]
	v_mfma_f32_16x16x32_bf16 v[90:93], v[220:223], v[188:191], v[90:93]
	v_mfma_f32_16x16x32_bf16 v[78:81], v[212:215], v[196:199], v[78:81]
	v_mfma_f32_16x16x32_bf16 v[74:77], v[220:223], v[196:199], v[74:77]
	v_mfma_f32_16x16x32_bf16 v[70:73], v[212:215], v[204:207], v[70:73]
	v_mfma_f32_16x16x32_bf16 v[66:69], v[220:223], v[204:207], v[66:69]
	s_barrier
	s_setprio 0
	s_add_i32 s17, s20, s35
	v_lshl_add_u64 v[224:225], v[224:225], 0, s[8:9]
	s_mov_b32 m0, s17
	s_nop 0
	global_load_lds_dwordx4 v[224:225], off
	v_lshl_add_u64 v[224:225], v[226:227], 0, s[8:9]
	s_add_i32 m0, s17, 0x2000
	s_nop 0
	global_load_lds_dwordx4 v[224:225], off
	s_mov_b32 m0, s54
	v_lshl_add_u64 v[224:225], v[228:229], 0, s[8:9]
	ds_read_b128 v[162:165], v143 offset:49152
	ds_read_b128 v[166:169], v143 offset:50176
	ds_read_b128 v[184:187], v143 offset:51200
	ds_read_b128 v[188:191], v143 offset:52224
	ds_read_b128 v[192:195], v143 offset:53248
	ds_read_b128 v[196:199], v143 offset:54272
	ds_read_b128 v[200:203], v143 offset:55296
	ds_read_b128 v[204:207], v143 offset:56320
	global_load_lds_dwordx4 v[224:225], off
	v_lshl_add_u64 v[224:225], v[234:235], 0, s[8:9]
	s_mov_b32 m0, s55
	s_nop 0
	global_load_lds_dwordx4 v[224:225], off
	s_add_u32 s14, s14, 0xb0080
	s_addc_u32 s15, s15, 0
	s_add_i32 s16, s16, s35
	v_lshl_add_u64 v[248:249], s[14:15], 0, v[176:177]
	s_mov_b32 m0, s16
	s_nop 0
	global_load_lds_dwordx4 v[248:249], off
	v_lshl_add_u64 v[248:249], s[14:15], 0, v[180:181]
	s_add_i32 m0, s16, 0x2000
	s_nop 0
	global_load_lds_dwordx4 v[248:249], off
	s_waitcnt vmcnt(8)
	s_waitcnt lgkmcnt(0)
	s_setprio 1
	s_barrier
	v_mfma_f32_16x16x32_bf16 v[62:65], v[146:149], v[162:165], v[62:65]
	v_mfma_f32_16x16x32_bf16 v[58:61], v[154:157], v[162:165], v[58:61]
	v_mfma_f32_16x16x32_bf16 v[54:57], v[146:149], v[184:187], v[54:57]
	v_mfma_f32_16x16x32_bf16 v[50:53], v[154:157], v[184:187], v[50:53]
	v_mfma_f32_16x16x32_bf16 v[38:41], v[146:149], v[192:195], v[38:41]
	v_mfma_f32_16x16x32_bf16 v[34:37], v[154:157], v[192:195], v[34:37]
	v_mfma_f32_16x16x32_bf16 v[22:25], v[146:149], v[200:203], v[22:25]
	v_mfma_f32_16x16x32_bf16 v[18:21], v[154:157], v[200:203], v[18:21]
	v_mfma_f32_16x16x32_bf16 v[62:65], v[150:153], v[166:169], v[62:65]
	v_mfma_f32_16x16x32_bf16 v[58:61], v[158:161], v[166:169], v[58:61]
	v_mfma_f32_16x16x32_bf16 v[54:57], v[150:153], v[188:191], v[54:57]
	v_mfma_f32_16x16x32_bf16 v[50:53], v[158:161], v[188:191], v[50:53]
	v_mfma_f32_16x16x32_bf16 v[38:41], v[150:153], v[196:199], v[38:41]
	v_mfma_f32_16x16x32_bf16 v[34:37], v[158:161], v[196:199], v[34:37]
	v_mfma_f32_16x16x32_bf16 v[22:25], v[150:153], v[204:207], v[22:25]
	v_mfma_f32_16x16x32_bf16 v[18:21], v[158:161], v[204:207], v[18:21]
	v_mfma_f32_16x16x32_bf16 v[46:49], v[208:211], v[162:165], v[46:49]
	v_mfma_f32_16x16x32_bf16 v[42:45], v[216:219], v[162:165], v[42:45]
	v_mfma_f32_16x16x32_bf16 v[30:33], v[208:211], v[184:187], v[30:33]
	v_mfma_f32_16x16x32_bf16 v[26:29], v[216:219], v[184:187], v[26:29]
	v_mfma_f32_16x16x32_bf16 v[14:17], v[208:211], v[192:195], v[14:17]
	v_mfma_f32_16x16x32_bf16 v[10:13], v[216:219], v[192:195], v[10:13]
	v_mfma_f32_16x16x32_bf16 v[6:9], v[208:211], v[200:203], v[6:9]
	v_mfma_f32_16x16x32_bf16 v[2:5], v[216:219], v[200:203], v[2:5]
	v_mfma_f32_16x16x32_bf16 v[46:49], v[212:215], v[166:169], v[46:49]
	v_mfma_f32_16x16x32_bf16 v[42:45], v[220:223], v[166:169], v[42:45]
	v_mfma_f32_16x16x32_bf16 v[30:33], v[212:215], v[188:191], v[30:33]
	v_mfma_f32_16x16x32_bf16 v[26:29], v[220:223], v[188:191], v[26:29]
	v_mfma_f32_16x16x32_bf16 v[14:17], v[212:215], v[196:199], v[14:17]
	v_mfma_f32_16x16x32_bf16 v[10:13], v[220:223], v[196:199], v[10:13]
	v_mfma_f32_16x16x32_bf16 v[6:9], v[212:215], v[204:207], v[6:9]
	v_mfma_f32_16x16x32_bf16 v[2:5], v[220:223], v[204:207], v[2:5]
	s_barrier
	s_setprio 0
	s_add_i32 s87, s87, 2
	s_add_u32 s12, s12, 0x100
	s_addc_u32 s13, s13, 0
	s_add_u32 s78, s78, 0x100
	s_addc_u32 s79, s79, 0
	s_cmp_gt_u32 s87, 19
.LBB0_869:
	ds_read_b128 v[146:149], v142
	ds_read_b128 v[150:153], v142 offset:1024
	ds_read_b128 v[154:157], v142 offset:2048
	ds_read_b128 v[158:161], v142 offset:3072
	s_add_u32 s14, s12, 0xfff50080
	s_addc_u32 s15, s13, -1
	s_cmp_eq_u32 s87, 18
	s_cselect_b32 s17, s1, s15
	s_cselect_b32 s16, s0, s14
	s_cselect_b32 s15, s7, s79
	s_cselect_b32 s14, s6, s78
	s_mov_b32 m0, s68
	v_lshl_add_u64 v[208:209], s[12:13], 0, v[132:133]
	ds_read_b128 v[162:165], v143
	ds_read_b128 v[166:169], v143 offset:1024
	ds_read_b128 v[184:187], v143 offset:2048
	ds_read_b128 v[188:191], v143 offset:3072
	ds_read_b128 v[192:195], v143 offset:4096
	ds_read_b128 v[196:199], v143 offset:5120
	ds_read_b128 v[200:203], v143 offset:6144
	ds_read_b128 v[204:207], v143 offset:7168
	global_load_lds_dwordx4 v[208:209], off
	v_lshl_add_u64 v[208:209], s[12:13], 0, v[134:135]
	s_mov_b32 m0, s69
	s_nop 0
	global_load_lds_dwordx4 v[208:209], off
	ds_read_b128 v[208:211], v144
	ds_read_b128 v[212:215], v144 offset:1024
	ds_read_b128 v[216:219], v144 offset:2048
	ds_read_b128 v[220:223], v144 offset:3072
	s_waitcnt vmcnt(8)
	s_waitcnt lgkmcnt(0)
	s_setprio 1
	s_barrier
	v_mfma_f32_16x16x32_bf16 v[126:129], v[146:149], v[162:165], v[126:129]
	v_mfma_f32_16x16x32_bf16 v[122:125], v[154:157], v[162:165], v[122:125]
	v_mfma_f32_16x16x32_bf16 v[118:121], v[146:149], v[184:187], v[118:121]
	v_mfma_f32_16x16x32_bf16 v[114:117], v[154:157], v[184:187], v[114:117]
	v_mfma_f32_16x16x32_bf16 v[102:105], v[146:149], v[192:195], v[102:105]
	v_mfma_f32_16x16x32_bf16 v[98:101], v[154:157], v[192:195], v[98:101]
	v_mfma_f32_16x16x32_bf16 v[86:89], v[146:149], v[200:203], v[86:89]
	v_mfma_f32_16x16x32_bf16 v[82:85], v[154:157], v[200:203], v[82:85]
	v_mfma_f32_16x16x32_bf16 v[126:129], v[150:153], v[166:169], v[126:129]
	v_mfma_f32_16x16x32_bf16 v[122:125], v[158:161], v[166:169], v[122:125]
	v_mfma_f32_16x16x32_bf16 v[118:121], v[150:153], v[188:191], v[118:121]
	v_mfma_f32_16x16x32_bf16 v[114:117], v[158:161], v[188:191], v[114:117]
	v_mfma_f32_16x16x32_bf16 v[102:105], v[150:153], v[196:199], v[102:105]
	v_mfma_f32_16x16x32_bf16 v[98:101], v[158:161], v[196:199], v[98:101]
	v_mfma_f32_16x16x32_bf16 v[86:89], v[150:153], v[204:207], v[86:89]
	v_mfma_f32_16x16x32_bf16 v[82:85], v[158:161], v[204:207], v[82:85]
	v_mfma_f32_16x16x32_bf16 v[110:113], v[208:211], v[162:165], v[110:113]
	v_mfma_f32_16x16x32_bf16 v[106:109], v[216:219], v[162:165], v[106:109]
	v_mfma_f32_16x16x32_bf16 v[94:97], v[208:211], v[184:187], v[94:97]
	v_mfma_f32_16x16x32_bf16 v[90:93], v[216:219], v[184:187], v[90:93]
	v_mfma_f32_16x16x32_bf16 v[78:81], v[208:211], v[192:195], v[78:81]
	v_mfma_f32_16x16x32_bf16 v[74:77], v[216:219], v[192:195], v[74:77]
	v_mfma_f32_16x16x32_bf16 v[70:73], v[208:211], v[200:203], v[70:73]
	v_mfma_f32_16x16x32_bf16 v[66:69], v[216:219], v[200:203], v[66:69]
	v_mfma_f32_16x16x32_bf16 v[110:113], v[212:215], v[166:169], v[110:113]
	v_mfma_f32_16x16x32_bf16 v[106:109], v[220:223], v[166:169], v[106:109]
	v_mfma_f32_16x16x32_bf16 v[94:97], v[212:215], v[188:191], v[94:97]
	v_mfma_f32_16x16x32_bf16 v[90:93], v[220:223], v[188:191], v[90:93]
	v_mfma_f32_16x16x32_bf16 v[78:81], v[212:215], v[196:199], v[78:81]
	v_mfma_f32_16x16x32_bf16 v[74:77], v[220:223], v[196:199], v[74:77]
	v_mfma_f32_16x16x32_bf16 v[70:73], v[212:215], v[204:207], v[70:73]
	v_mfma_f32_16x16x32_bf16 v[66:69], v[220:223], v[204:207], v[66:69]
	s_barrier
	s_setprio 0
	s_mov_b32 m0, s70
	v_lshl_add_u64 v[224:225], s[14:15], 0, v[176:177]
	global_load_lds_dwordx4 v[224:225], off
	v_lshl_add_u64 v[226:227], s[14:15], 0, v[180:181]
	s_mov_b32 m0, s71
	s_nop 0
	global_load_lds_dwordx4 v[226:227], off
	s_mov_b32 m0, s40
	v_lshl_add_u64 v[228:229], s[16:17], 0, v[172:173]
	ds_read_b128 v[162:165], v143 offset:16384
	ds_read_b128 v[166:169], v143 offset:17408
	ds_read_b128 v[184:187], v143 offset:18432
	ds_read_b128 v[188:191], v143 offset:19456
	ds_read_b128 v[192:195], v143 offset:20480
	ds_read_b128 v[196:199], v143 offset:21504
	ds_read_b128 v[200:203], v143 offset:22528
	ds_read_b128 v[204:207], v143 offset:23552
	global_load_lds_dwordx4 v[228:229], off
	v_lshl_add_u64 v[234:235], s[16:17], 0, v[178:179]
	s_mov_b32 m0, s41
	s_nop 0
	global_load_lds_dwordx4 v[234:235], off
	s_add_u32 s20, s14, 0xb0000
	s_addc_u32 s21, s15, 0
	s_add_i32 s60, s56, s35
	v_lshl_add_u64 v[246:247], s[20:21], 0, v[176:177]
	s_mov_b32 m0, s60
	s_nop 0
	global_load_lds_dwordx4 v[246:247], off
	v_lshl_add_u64 v[246:247], s[20:21], 0, v[180:181]
	s_add_i32 m0, s60, 0x2000
	s_nop 0
	global_load_lds_dwordx4 v[246:247], off
	s_waitcnt vmcnt(8)
	s_waitcnt lgkmcnt(0)
	s_setprio 1
	s_barrier
	v_mfma_f32_16x16x32_bf16 v[62:65], v[146:149], v[162:165], v[62:65]
	v_mfma_f32_16x16x32_bf16 v[58:61], v[154:157], v[162:165], v[58:61]
	v_mfma_f32_16x16x32_bf16 v[54:57], v[146:149], v[184:187], v[54:57]
	v_mfma_f32_16x16x32_bf16 v[50:53], v[154:157], v[184:187], v[50:53]
	v_mfma_f32_16x16x32_bf16 v[38:41], v[146:149], v[192:195], v[38:41]
	v_mfma_f32_16x16x32_bf16 v[34:37], v[154:157], v[192:195], v[34:37]
	v_mfma_f32_16x16x32_bf16 v[22:25], v[146:149], v[200:203], v[22:25]
	v_mfma_f32_16x16x32_bf16 v[18:21], v[154:157], v[200:203], v[18:21]
	v_mfma_f32_16x16x32_bf16 v[62:65], v[150:153], v[166:169], v[62:65]
	v_mfma_f32_16x16x32_bf16 v[58:61], v[158:161], v[166:169], v[58:61]
	v_mfma_f32_16x16x32_bf16 v[54:57], v[150:153], v[188:191], v[54:57]
	v_mfma_f32_16x16x32_bf16 v[50:53], v[158:161], v[188:191], v[50:53]
	v_mfma_f32_16x16x32_bf16 v[38:41], v[150:153], v[196:199], v[38:41]
	v_mfma_f32_16x16x32_bf16 v[34:37], v[158:161], v[196:199], v[34:37]
	v_mfma_f32_16x16x32_bf16 v[22:25], v[150:153], v[204:207], v[22:25]
	v_mfma_f32_16x16x32_bf16 v[18:21], v[158:161], v[204:207], v[18:21]
	v_mfma_f32_16x16x32_bf16 v[46:49], v[208:211], v[162:165], v[46:49]
	v_mfma_f32_16x16x32_bf16 v[42:45], v[216:219], v[162:165], v[42:45]
	v_mfma_f32_16x16x32_bf16 v[30:33], v[208:211], v[184:187], v[30:33]
	v_mfma_f32_16x16x32_bf16 v[26:29], v[216:219], v[184:187], v[26:29]
	v_mfma_f32_16x16x32_bf16 v[14:17], v[208:211], v[192:195], v[14:17]
	v_mfma_f32_16x16x32_bf16 v[10:13], v[216:219], v[192:195], v[10:13]
	v_mfma_f32_16x16x32_bf16 v[6:9], v[208:211], v[200:203], v[6:9]
	v_mfma_f32_16x16x32_bf16 v[2:5], v[216:219], v[200:203], v[2:5]
	v_mfma_f32_16x16x32_bf16 v[46:49], v[212:215], v[166:169], v[46:49]
	v_mfma_f32_16x16x32_bf16 v[42:45], v[220:223], v[166:169], v[42:45]
	v_mfma_f32_16x16x32_bf16 v[30:33], v[212:215], v[188:191], v[30:33]
	v_mfma_f32_16x16x32_bf16 v[26:29], v[220:223], v[188:191], v[26:29]
	v_mfma_f32_16x16x32_bf16 v[14:17], v[212:215], v[196:199], v[14:17]
	v_mfma_f32_16x16x32_bf16 v[10:13], v[220:223], v[196:199], v[10:13]
	v_mfma_f32_16x16x32_bf16 v[6:9], v[212:215], v[204:207], v[6:9]
	v_mfma_f32_16x16x32_bf16 v[2:5], v[220:223], v[204:207], v[2:5]
	s_barrier
	s_setprio 0
	s_add_i32 s20, 0, 0x18000
	v_add_u32_e32 v145, s20, v141
	ds_read_b128 v[146:149], v145
	ds_read_b128 v[150:153], v145 offset:1024
	ds_read_b128 v[154:157], v145 offset:2048
	ds_read_b128 v[158:161], v145 offset:3072
	s_add_u32 s16, s16, 0xb0000
	s_addc_u32 s17, s17, 0
	s_mov_b32 m0, s48
	v_lshl_add_u64 v[208:209], s[16:17], 0, v[172:173]
	ds_read_b128 v[162:165], v143 offset:32768
	ds_read_b128 v[166:169], v143 offset:33792
	ds_read_b128 v[184:187], v143 offset:34816
	ds_read_b128 v[188:191], v143 offset:35840
	ds_read_b128 v[192:195], v143 offset:36864
	ds_read_b128 v[196:199], v143 offset:37888
	ds_read_b128 v[200:203], v143 offset:38912
	ds_read_b128 v[204:207], v143 offset:39936
	global_load_lds_dwordx4 v[208:209], off
	v_lshl_add_u64 v[208:209], s[16:17], 0, v[178:179]
	s_mov_b32 m0, s49
	s_nop 0
	global_load_lds_dwordx4 v[208:209], off
	s_add_i32 s16, 0, 0x1c000
	v_add_u32_e32 v145, s16, v141
	ds_read_b128 v[208:211], v145
	ds_read_b128 v[212:215], v145 offset:1024
	ds_read_b128 v[216:219], v145 offset:2048
	ds_read_b128 v[220:223], v145 offset:3072
	s_waitcnt vmcnt(8)
	s_waitcnt lgkmcnt(0)
	s_setprio 1
	s_barrier
	v_mfma_f32_16x16x32_bf16 v[126:129], v[146:149], v[162:165], v[126:129]
	v_mfma_f32_16x16x32_bf16 v[122:125], v[154:157], v[162:165], v[122:125]
	v_mfma_f32_16x16x32_bf16 v[118:121], v[146:149], v[184:187], v[118:121]
	v_mfma_f32_16x16x32_bf16 v[114:117], v[154:157], v[184:187], v[114:117]
	v_mfma_f32_16x16x32_bf16 v[102:105], v[146:149], v[192:195], v[102:105]
	v_mfma_f32_16x16x32_bf16 v[98:101], v[154:157], v[192:195], v[98:101]
	v_mfma_f32_16x16x32_bf16 v[86:89], v[146:149], v[200:203], v[86:89]
	v_mfma_f32_16x16x32_bf16 v[82:85], v[154:157], v[200:203], v[82:85]
	v_mfma_f32_16x16x32_bf16 v[126:129], v[150:153], v[166:169], v[126:129]
	v_mfma_f32_16x16x32_bf16 v[122:125], v[158:161], v[166:169], v[122:125]
	v_mfma_f32_16x16x32_bf16 v[118:121], v[150:153], v[188:191], v[118:121]
	v_mfma_f32_16x16x32_bf16 v[114:117], v[158:161], v[188:191], v[114:117]
	v_mfma_f32_16x16x32_bf16 v[102:105], v[150:153], v[196:199], v[102:105]
	v_mfma_f32_16x16x32_bf16 v[98:101], v[158:161], v[196:199], v[98:101]
	v_mfma_f32_16x16x32_bf16 v[86:89], v[150:153], v[204:207], v[86:89]
	v_mfma_f32_16x16x32_bf16 v[82:85], v[158:161], v[204:207], v[82:85]
	v_mfma_f32_16x16x32_bf16 v[110:113], v[208:211], v[162:165], v[110:113]
	v_mfma_f32_16x16x32_bf16 v[106:109], v[216:219], v[162:165], v[106:109]
	v_mfma_f32_16x16x32_bf16 v[94:97], v[208:211], v[184:187], v[94:97]
	v_mfma_f32_16x16x32_bf16 v[90:93], v[216:219], v[184:187], v[90:93]
	v_mfma_f32_16x16x32_bf16 v[78:81], v[208:211], v[192:195], v[78:81]
	v_mfma_f32_16x16x32_bf16 v[74:77], v[216:219], v[192:195], v[74:77]
	v_mfma_f32_16x16x32_bf16 v[70:73], v[208:211], v[200:203], v[70:73]
	v_mfma_f32_16x16x32_bf16 v[66:69], v[216:219], v[200:203], v[66:69]
	v_mfma_f32_16x16x32_bf16 v[110:113], v[212:215], v[166:169], v[110:113]
	v_mfma_f32_16x16x32_bf16 v[106:109], v[220:223], v[166:169], v[106:109]
	v_mfma_f32_16x16x32_bf16 v[94:97], v[212:215], v[188:191], v[94:97]
	v_mfma_f32_16x16x32_bf16 v[90:93], v[220:223], v[188:191], v[90:93]
	v_mfma_f32_16x16x32_bf16 v[78:81], v[212:215], v[196:199], v[78:81]
	v_mfma_f32_16x16x32_bf16 v[74:77], v[220:223], v[196:199], v[74:77]
	v_mfma_f32_16x16x32_bf16 v[70:73], v[212:215], v[204:207], v[70:73]
	v_mfma_f32_16x16x32_bf16 v[66:69], v[220:223], v[204:207], v[66:69]
	s_barrier
	s_setprio 0
	s_add_i32 s17, s20, s35
	v_lshl_add_u64 v[224:225], v[224:225], 0, s[8:9]
	s_mov_b32 m0, s17
	s_nop 0
	global_load_lds_dwordx4 v[224:225], off
	v_lshl_add_u64 v[224:225], v[226:227], 0, s[8:9]
	s_add_i32 m0, s17, 0x2000
	s_nop 0
	global_load_lds_dwordx4 v[224:225], off
	s_mov_b32 m0, s54
	v_lshl_add_u64 v[224:225], v[228:229], 0, s[8:9]
	ds_read_b128 v[162:165], v143 offset:49152
	ds_read_b128 v[166:169], v143 offset:50176
	ds_read_b128 v[184:187], v143 offset:51200
	ds_read_b128 v[188:191], v143 offset:52224
	ds_read_b128 v[192:195], v143 offset:53248
	ds_read_b128 v[196:199], v143 offset:54272
	ds_read_b128 v[200:203], v143 offset:55296
	ds_read_b128 v[204:207], v143 offset:56320
	global_load_lds_dwordx4 v[224:225], off
	v_lshl_add_u64 v[224:225], v[234:235], 0, s[8:9]
	s_mov_b32 m0, s55
	s_nop 0
	global_load_lds_dwordx4 v[224:225], off
	s_add_u32 s14, s14, 0xb0080
	s_addc_u32 s15, s15, 0
	s_add_i32 s16, s16, s35
	v_lshl_add_u64 v[248:249], s[14:15], 0, v[176:177]
	s_mov_b32 m0, s16
	s_nop 0
	global_load_lds_dwordx4 v[248:249], off
	v_lshl_add_u64 v[248:249], s[14:15], 0, v[180:181]
	s_add_i32 m0, s16, 0x2000
	s_nop 0
	global_load_lds_dwordx4 v[248:249], off
	s_waitcnt vmcnt(8)
	s_waitcnt lgkmcnt(0)
	s_setprio 1
	s_barrier
	v_mfma_f32_16x16x32_bf16 v[62:65], v[146:149], v[162:165], v[62:65]
	v_mfma_f32_16x16x32_bf16 v[58:61], v[154:157], v[162:165], v[58:61]
	v_mfma_f32_16x16x32_bf16 v[54:57], v[146:149], v[184:187], v[54:57]
	v_mfma_f32_16x16x32_bf16 v[50:53], v[154:157], v[184:187], v[50:53]
	v_mfma_f32_16x16x32_bf16 v[38:41], v[146:149], v[192:195], v[38:41]
	v_mfma_f32_16x16x32_bf16 v[34:37], v[154:157], v[192:195], v[34:37]
	v_mfma_f32_16x16x32_bf16 v[22:25], v[146:149], v[200:203], v[22:25]
	v_mfma_f32_16x16x32_bf16 v[18:21], v[154:157], v[200:203], v[18:21]
	v_mfma_f32_16x16x32_bf16 v[62:65], v[150:153], v[166:169], v[62:65]
	v_mfma_f32_16x16x32_bf16 v[58:61], v[158:161], v[166:169], v[58:61]
	v_mfma_f32_16x16x32_bf16 v[54:57], v[150:153], v[188:191], v[54:57]
	v_mfma_f32_16x16x32_bf16 v[50:53], v[158:161], v[188:191], v[50:53]
	v_mfma_f32_16x16x32_bf16 v[38:41], v[150:153], v[196:199], v[38:41]
	v_mfma_f32_16x16x32_bf16 v[34:37], v[158:161], v[196:199], v[34:37]
	v_mfma_f32_16x16x32_bf16 v[22:25], v[150:153], v[204:207], v[22:25]
	v_mfma_f32_16x16x32_bf16 v[18:21], v[158:161], v[204:207], v[18:21]
	v_mfma_f32_16x16x32_bf16 v[46:49], v[208:211], v[162:165], v[46:49]
	v_mfma_f32_16x16x32_bf16 v[42:45], v[216:219], v[162:165], v[42:45]
	v_mfma_f32_16x16x32_bf16 v[30:33], v[208:211], v[184:187], v[30:33]
	v_mfma_f32_16x16x32_bf16 v[26:29], v[216:219], v[184:187], v[26:29]
	v_mfma_f32_16x16x32_bf16 v[14:17], v[208:211], v[192:195], v[14:17]
	v_mfma_f32_16x16x32_bf16 v[10:13], v[216:219], v[192:195], v[10:13]
	v_mfma_f32_16x16x32_bf16 v[6:9], v[208:211], v[200:203], v[6:9]
	v_mfma_f32_16x16x32_bf16 v[2:5], v[216:219], v[200:203], v[2:5]
	v_mfma_f32_16x16x32_bf16 v[46:49], v[212:215], v[166:169], v[46:49]
	v_mfma_f32_16x16x32_bf16 v[42:45], v[220:223], v[166:169], v[42:45]
	v_mfma_f32_16x16x32_bf16 v[30:33], v[212:215], v[188:191], v[30:33]
	v_mfma_f32_16x16x32_bf16 v[26:29], v[220:223], v[188:191], v[26:29]
	v_mfma_f32_16x16x32_bf16 v[14:17], v[212:215], v[196:199], v[14:17]
	v_mfma_f32_16x16x32_bf16 v[10:13], v[220:223], v[196:199], v[10:13]
	v_mfma_f32_16x16x32_bf16 v[6:9], v[212:215], v[204:207], v[6:9]
	v_mfma_f32_16x16x32_bf16 v[2:5], v[220:223], v[204:207], v[2:5]
	s_barrier
	s_setprio 0
	s_add_i32 s87, s87, 2
	s_add_u32 s12, s12, 0x100
	s_addc_u32 s13, s13, 0
	s_add_u32 s78, s78, 0x100
	s_addc_u32 s79, s79, 0
	s_cmp_gt_u32 s87, 19
	s_cbranch_scc0 .LBB0_869
	s_cmp_eq_u32 s75, 0
	s_cselect_b32 s12, 0, 0x800000
	s_add_u32 s14, s51, s12
	s_addc_u32 s15, s53, 0
	s_lshl_b32 s12, s77, 8
	s_ashr_i32 s13, s12, 31
	s_lshl_b64 s[12:13], s[12:13], 1
	s_add_u32 s12, s14, s12
	v_lshl_add_u32 v148, s76, 8, v140
	s_addc_u32 s13, s15, s13
	v_ashrrev_i32_e32 v149, 31, v148
	v_lshl_add_u64 v[146:147], s[12:13], 0, v[130:131]
	v_lshlrev_b64 v[150:151], 11, v[148:149]
	v_cvt_pk_bf16_f32 v110, v110, v111
	v_cvt_pk_bf16_f32 v111, v112, v113
	v_cvt_pk_bf16_f32 v112, v106, v107
	v_or_b32_e32 v106, 16, v148
	v_cvt_pk_bf16_f32 v46, v46, v47
	v_cvt_pk_bf16_f32 v47, v48, v49
	v_cvt_pk_bf16_f32 v48, v42, v43
	v_add_u32_e32 v42, 0x90, v148
	v_lshl_add_u64 v[150:151], v[146:147], 0, v[150:151]
	v_ashrrev_i32_e32 v107, 31, v106
	v_cvt_pk_bf16_f32 v94, v94, v95
	v_cvt_pk_bf16_f32 v95, v96, v97
	v_cvt_pk_bf16_f32 v96, v90, v91
	v_or_b32_e32 v90, 32, v148
	v_ashrrev_i32_e32 v43, 31, v42
	v_cvt_pk_bf16_f32 v30, v30, v31
	v_cvt_pk_bf16_f32 v31, v32, v33
	v_cvt_pk_bf16_f32 v32, v26, v27
	v_add_u32_e32 v26, 0xa0, v148
	v_cvt_pk_bf16_f32 v113, v108, v109
	v_lshlrev_b64 v[106:107], 11, v[106:107]
	v_ashrrev_i32_e32 v91, 31, v90
	v_cvt_pk_bf16_f32 v78, v78, v79
	v_cvt_pk_bf16_f32 v79, v80, v81
	v_cvt_pk_bf16_f32 v80, v74, v75
	v_or_b32_e32 v74, 48, v148
	v_cvt_pk_bf16_f32 v70, v70, v71
	v_cvt_pk_bf16_f32 v71, v72, v73
	v_cvt_pk_bf16_f32 v72, v66, v67
	v_lshl_add_u64 v[66:67], v[150:151], 0, s[10:11]
	v_cvt_pk_bf16_f32 v49, v44, v45
	v_lshlrev_b64 v[42:43], 11, v[42:43]
	v_ashrrev_i32_e32 v27, 31, v26
	v_cvt_pk_bf16_f32 v14, v14, v15
	v_cvt_pk_bf16_f32 v15, v16, v17
	v_cvt_pk_bf16_f32 v16, v10, v11
	v_add_u32_e32 v10, 0xb0, v148
	global_store_dwordx4 v[150:151], v[110:113], off offset:256 nt
	v_cvt_pk_bf16_f32 v97, v92, v93
	v_lshlrev_b64 v[90:91], 11, v[90:91]
	v_lshl_add_u64 v[110:111], v[146:147], 0, v[106:107]
	v_ashrrev_i32_e32 v75, 31, v74
	v_cvt_pk_bf16_f32 v62, v62, v63
	v_cvt_pk_bf16_f32 v63, v64, v65
	v_cvt_pk_bf16_f32 v64, v58, v59
	v_add_co_u32_e32 v58, vcc, s57, v150
	global_store_dwordx4 v[66:67], v[46:49], off offset:256 nt
	v_cvt_pk_bf16_f32 v33, v28, v29
	v_lshlrev_b64 v[26:27], 11, v[26:27]
	v_lshl_add_u64 v[46:47], v[146:147], 0, v[42:43]
	v_ashrrev_i32_e32 v11, 31, v10
	global_store_dwordx4 v[110:111], v[94:97], off offset:256 nt
	v_cvt_pk_bf16_f32 v81, v76, v77
	v_lshlrev_b64 v[74:75], 11, v[74:75]
	v_lshl_add_u64 v[94:95], v[146:147], 0, v[90:91]
	v_addc_co_u32_e32 v59, vcc, 0, v151, vcc
	global_store_dwordx4 v[46:47], v[30:33], off offset:256 nt
	v_cvt_pk_bf16_f32 v17, v12, v13
	v_lshlrev_b64 v[10:11], 11, v[10:11]
	v_lshl_add_u64 v[30:31], v[146:147], 0, v[26:27]
	v_cvt_pk_bf16_f32 v126, v126, v127
	v_cvt_pk_bf16_f32 v127, v128, v129
	v_cvt_pk_bf16_f32 v128, v122, v123
	v_cvt_pk_bf16_f32 v129, v124, v125
	v_cvt_pk_bf16_f32 v106, v118, v119
	v_cvt_pk_bf16_f32 v107, v120, v121
	v_cvt_pk_bf16_f32 v108, v114, v115
	v_cvt_pk_bf16_f32 v109, v116, v117
	v_cvt_pk_bf16_f32 v90, v102, v103
	v_cvt_pk_bf16_f32 v91, v104, v105
	v_cvt_pk_bf16_f32 v92, v98, v99
	v_cvt_pk_bf16_f32 v93, v100, v101
	global_store_dwordx4 v[94:95], v[78:81], off offset:256 nt
	v_cvt_pk_bf16_f32 v76, v82, v83
	v_cvt_pk_bf16_f32 v77, v84, v85
	v_lshl_add_u64 v[78:79], v[146:147], 0, v[74:75]
	v_cvt_pk_bf16_f32 v74, v86, v87
	v_cvt_pk_bf16_f32 v75, v88, v89
	v_cvt_pk_bf16_f32 v73, v68, v69
	v_cvt_pk_bf16_f32 v65, v60, v61
	v_cvt_pk_bf16_f32 v42, v54, v55
	v_cvt_pk_bf16_f32 v43, v56, v57
	v_cvt_pk_bf16_f32 v44, v50, v51
	v_cvt_pk_bf16_f32 v45, v52, v53
	v_cvt_pk_bf16_f32 v26, v38, v39
	v_cvt_pk_bf16_f32 v27, v40, v41
	v_cvt_pk_bf16_f32 v28, v34, v35
	v_cvt_pk_bf16_f32 v29, v36, v37
	global_store_dwordx4 v[30:31], v[14:17], off offset:256 nt
	v_cvt_pk_bf16_f32 v12, v18, v19
	v_cvt_pk_bf16_f32 v13, v20, v21
	v_lshl_add_u64 v[14:15], v[146:147], 0, v[10:11]
	v_cvt_pk_bf16_f32 v10, v22, v23
	v_cvt_pk_bf16_f32 v11, v24, v25
	v_cvt_pk_bf16_f32 v6, v6, v7
	v_cvt_pk_bf16_f32 v7, v8, v9
	v_cvt_pk_bf16_f32 v8, v2, v3
	v_cvt_pk_bf16_f32 v9, v4, v5
	s_and_b64 vcc, exec, s[4:5]
	s_mov_b32 s75, s72
	s_mov_b32 s77, s73
	s_mov_b32 s76, s74
	s_mov_b64 s[14:15], s[6:7]
	s_mov_b64 s[12:13], s[0:1]
	global_store_dwordx4 v[150:151], v[126:129], off nt
	global_store_dwordx4 v[110:111], v[106:109], off nt
	global_store_dwordx4 v[94:95], v[90:93], off nt
	global_store_dwordx4 v[78:79], v[74:77], off nt
	global_store_dwordx4 v[78:79], v[70:73], off offset:256 nt
	global_store_dwordx4 v[58:59], v[62:65], off nt
	global_store_dwordx4 v[46:47], v[42:45], off nt
	global_store_dwordx4 v[30:31], v[26:29], off nt
	global_store_dwordx4 v[14:15], v[10:13], off nt
	global_store_dwordx4 v[14:15], v[6:9], off offset:256 nt
	s_cbranch_vccz .LBB0_862
	s_waitcnt vmcnt(0)
	s_cmpk_gt_u32 s34, 0xff
	s_cbranch_scc1 .LBB0_873
	s_barrier

.LBB0_1367:
	s_add_u32 s0, s30, 0x1a2d800
	s_addc_u32 s1, s31, 0
	s_add_u32 s77, s30, 0xa9000
	s_addc_u32 s78, s31, 0
	s_add_u32 s6, s30, 0x19c800
	s_addc_u32 s7, s31, 0
	s_add_u32 s8, s30, 0x9b00000
	s_addc_u32 s9, s31, 0
	s_add_u32 s10, s30, 0x10700000
	s_addc_u32 s11, s31, 0
	s_add_u32 s12, s30, 0x12700000
	s_addc_u32 s13, s31, 0
	s_add_u32 s14, s30, 0x14700000
	s_addc_u32 s15, s31, 0
	s_add_u32 s16, s30, 0x1b00000
	s_addc_u32 s17, s31, 0
	s_add_u32 s79, s30, 0xbf00000
	s_addc_u32 s87, s31, 0
	s_add_u32 s89, s30, 0xe300000
	s_mov_b64 s[24:25], 0x80
	s_addc_u32 s92, s31, 0
	s_and_b32 s3, s19, 3
	s_add_i32 m0, s72, 0x18000
	v_lshl_add_u64 v[8:9], v[8:9], 0, s[24:25]
	s_ashr_i32 s93, s22, 31
	s_lshl_b32 s94, s18, 6
	s_lshl_b32 s5, s18, 13
	s_lshl_b32 s20, s3, 12
	s_waitcnt vmcnt(0)
	s_barrier
	global_load_lds_dwordx4 v[8:9], off
	v_lshl_add_u64 v[6:7], v[6:7], 0, s[24:25]
	s_add_i32 m0, s72, 0x1a000
	s_add_i32 s95, s72, 0x8000
	s_add_i32 s96, s72, 0xa000
	global_load_lds_dwordx4 v[6:7], off
	v_lshl_add_u64 v[4:5], v[4:5], 0, s[24:25]
	s_mov_b32 m0, s95
	s_add_u32 s18, s54, 0x40080
	global_load_lds_dwordx4 v[4:5], off
	v_lshl_add_u64 v[2:3], v[2:3], 0, s[24:25]
	s_mov_b32 m0, s96
	s_addc_u32 s19, s55, 0
	global_load_lds_dwordx4 v[2:3], off
	s_add_i32 m0, s72, 0x1c000
	v_lshl_add_u64 v[2:3], s[18:19], 0, v[164:165]
	global_load_lds_dwordx4 v[2:3], off
	v_lshl_add_u64 v[2:3], s[18:19], 0, v[168:169]
	s_add_i32 m0, s72, 0x1e000
	v_lshlrev_b32_e32 v4, 6, v170
	global_load_lds_dwordx4 v[2:3], off
	v_bfe_u32 v2, v170, 4, 2
	v_lshlrev_b32_e32 v3, 3, v2
	v_lshlrev_b32_e32 v2, 4, v2
	s_movk_i32 s18, 0x3c0
	v_lshlrev_b32_e32 v5, 2, v170
	v_and_or_b32 v4, v4, s18, v2
	v_and_b32_e32 v5, 32, v5
	v_lshl_or_b32 v224, s3, 5, v3
	v_lshlrev_b32_e32 v3, 8, v170
	v_bitop3_b32 v175, s20, v4, v5 bitop3:0xf6
	v_and_b32_e32 v3, 0x38000, v3
	v_lshlrev_b32_e32 v4, 11, v12
	v_or3_b32 v3, v10, v3, v4
	v_lshlrev_b32_e32 v6, 2, v171
	v_add_u32_e32 v178, v3, v11
	v_lshlrev_b32_e32 v3, 4, v13
	v_lshl_or_b32 v2, v171, 6, v2
	v_and_b32_e32 v6, 32, v6
	s_waitcnt vmcnt(6)
	v_and_b32_e32 v3, 0x78000, v3
	v_bitop3_b32 v2, v2, s5, v6 bitop3:0xde
	v_or3_b32 v3, v10, v3, v4
	s_add_i32 s33, 0, 0x10000
	s_add_i32 s64, 0, 0x14000
	s_mov_b32 s97, s22
	v_mov_b32_e32 v179, v177
	v_add_u32_e32 v180, v3, v11
	v_mov_b32_e32 v181, v177
	v_mov_b64_e32 v[182:183], 0xbff
	v_add_u32_e32 v225, s33, v175
	v_add_u32_e32 v226, 0, v2
	v_add_u32_e32 v227, s64, v175
	v_mov_b64_e32 v[184:185], 0x5f
	v_mov_b32_e32 v228, 0x80
	s_barrier
	s_branch .LBB0_1369

.LBB0_2615:
	s_sext_i32_i8 s67, s0
	s_add_u32 s0, s30, 0x1b00000
	v_bfe_u32 v1, v170, 4, 2
	s_addc_u32 s1, s31, 0
	s_waitcnt vmcnt(0)
	v_lshlrev_b32_e32 v14, 3, v1
	v_lshlrev_b32_e32 v15, 4, v1
	v_lshlrev_b32_e32 v1, 6, v170
	s_movk_i32 s6, 0x3c0
	s_add_u32 s4, s30, 0x15b00000
	v_and_b32_e32 v13, 15, v170
	v_and_or_b32 v16, v1, s6, v15
	v_lshlrev_b32_e32 v1, 2, v170
	s_mov_b64 s[6:7], 0x80
	s_addc_u32 s5, s31, 0
	v_and_b32_e32 v17, 32, v1
	s_and_b32 s8, s3, 3
	v_lshl_or_b32 v1, s2, 6, v13
	v_lshl_or_b32 v13, v13, 6, v15
	s_lshl_b32 s2, s2, 13
	s_add_i32 m0, s50, 0x18000
	v_lshl_add_u64 v[8:9], v[8:9], 0, s[6:7]
	v_bitop3_b32 v13, v13, s2, v17 bitop3:0xde
	s_lshl_b32 s2, s8, 12
	s_waitcnt vmcnt(0)
	s_barrier
	global_load_lds_dwordx4 v[8:9], off
	v_lshl_add_u64 v[6:7], v[6:7], 0, s[6:7]
	s_add_i32 m0, s50, 0x1a000
	s_add_i32 s55, s50, 0x8000
	s_add_i32 s56, s50, 0xa000
	v_bitop3_b32 v161, s2, v16, v17 bitop3:0xf6
	global_load_lds_dwordx4 v[6:7], off
	v_lshl_add_u64 v[4:5], v[4:5], 0, s[6:7]
	s_mov_b32 m0, s55
	s_add_u32 s2, s42, 0x40080
	global_load_lds_dwordx4 v[4:5], off
	v_lshl_add_u64 v[2:3], v[2:3], 0, s[6:7]
	s_mov_b32 m0, s56
	s_addc_u32 s3, s43, 0
	global_load_lds_dwordx4 v[2:3], off
	s_add_i32 m0, s50, 0x1c000
	v_lshl_add_u64 v[2:3], s[2:3], 0, v[152:153]
	global_load_lds_dwordx4 v[2:3], off
	v_lshl_add_u64 v[2:3], s[2:3], 0, v[156:157]
	s_add_i32 m0, s50, 0x1e000
	v_lshl_or_b32 v160, s8, 5, v14
	global_load_lds_dwordx4 v[2:3], off
	v_lshlrev_b32_e32 v2, 8, v170
	v_and_b32_e32 v2, 0x38000, v2
	v_lshlrev_b32_e32 v3, 11, v231
	v_or3_b32 v2, v10, v2, v3
	v_add_u32_e32 v164, v2, v11
	v_lshlrev_b32_e32 v2, 4, v12
	s_waitcnt vmcnt(6)
	v_and_b32_e32 v2, 0x78000, v2
	v_lshlrev_b32_e32 v158, 1, v160
	v_or3_b32 v2, v10, v2, v3
	v_lshl_add_u64 v[162:163], s[0:1], 0, v[158:159]
	v_mov_b32_e32 v165, v159
	v_add_u32_e32 v166, v2, v11
	v_mov_b32_e32 v167, v159
	v_mov_b64_e32 v[168:169], 0x200
	v_mov_b64_e32 v[174:175], 0x1ff
	s_add_i32 s57, 0, 0x10000
	v_add_u32_e32 v171, 0, v13
	s_add_i32 s60, 0, 0x14000
	s_mov_b64 s[8:9], 0x80000
	s_mov_b32 s61, 0x80000
	s_mov_b64 s[10:11], 0x90000
	s_mov_b32 s62, 0x90000
	s_mov_b64 s[12:13], 0xa0000
	s_mov_b32 s63, 0xa0000
	s_mov_b64 s[14:15], 0xb0000
	s_mov_b32 s64, 0xb0000
	v_mov_b32_e32 v2, v159
	v_mov_b32_e32 v3, v159
	v_mov_b32_e32 v4, v159
	v_mov_b32_e32 v5, v159
	v_mov_b32_e32 v6, v159
	v_mov_b32_e32 v7, v159
	v_mov_b32_e32 v8, v159
	v_mov_b32_e32 v9, v159
	v_mov_b32_e32 v10, v159
	v_mov_b32_e32 v11, v159
	v_mov_b32_e32 v12, v159
	v_mov_b32_e32 v13, v159
	v_mov_b32_e32 v14, v159
	v_mov_b32_e32 v15, v159
	v_mov_b32_e32 v16, v159
	v_mov_b32_e32 v17, v159
	v_mov_b32_e32 v18, v159
	v_mov_b32_e32 v19, v159
	v_mov_b32_e32 v20, v159
	v_mov_b32_e32 v21, v159
	v_mov_b32_e32 v22, v159
	v_mov_b32_e32 v23, v159
	v_mov_b32_e32 v24, v159
	v_mov_b32_e32 v25, v159
	v_mov_b32_e32 v26, v159
	v_mov_b32_e32 v27, v159
	v_mov_b32_e32 v28, v159
	v_mov_b32_e32 v29, v159
	v_mov_b32_e32 v30, v159
	v_mov_b32_e32 v31, v159
	v_mov_b32_e32 v32, v159
	v_mov_b32_e32 v33, v159
	v_mov_b32_e32 v34, v159
	v_mov_b32_e32 v35, v159
	v_mov_b32_e32 v36, v159
	v_mov_b32_e32 v37, v159
	v_mov_b32_e32 v38, v159
	v_mov_b32_e32 v39, v159
	v_mov_b32_e32 v40, v159
	v_mov_b32_e32 v41, v159
	v_mov_b32_e32 v42, v159
	v_mov_b32_e32 v43, v159
	v_mov_b32_e32 v44, v159
	v_mov_b32_e32 v45, v159
	v_mov_b32_e32 v46, v159
	v_mov_b32_e32 v47, v159
	v_mov_b32_e32 v48, v159
	v_mov_b32_e32 v49, v159
	v_mov_b32_e32 v50, v159
	v_mov_b32_e32 v51, v159
	v_mov_b32_e32 v52, v159
	v_mov_b32_e32 v53, v159
	v_mov_b32_e32 v54, v159
	v_mov_b32_e32 v55, v159
	v_mov_b32_e32 v56, v159
	v_mov_b32_e32 v57, v159
	v_mov_b32_e32 v58, v159
	v_mov_b32_e32 v59, v159
	v_mov_b32_e32 v60, v159
	v_mov_b32_e32 v61, v159
	v_mov_b32_e32 v62, v159
	v_mov_b32_e32 v63, v159
	v_mov_b32_e32 v64, v159
	v_mov_b32_e32 v65, v159
	v_mov_b32_e32 v66, v159
	v_mov_b32_e32 v67, v159
	v_mov_b32_e32 v68, v159
	v_mov_b32_e32 v69, v159
	v_mov_b32_e32 v70, v159
	v_mov_b32_e32 v71, v159
	v_mov_b32_e32 v72, v159
	v_mov_b32_e32 v73, v159
	v_mov_b32_e32 v74, v159
	v_mov_b32_e32 v75, v159
	v_mov_b32_e32 v76, v159
	v_mov_b32_e32 v77, v159
	v_mov_b32_e32 v78, v159
	v_mov_b32_e32 v79, v159
	v_mov_b32_e32 v80, v159
	v_mov_b32_e32 v81, v159
	v_mov_b32_e32 v82, v159
	v_mov_b32_e32 v83, v159
	v_mov_b32_e32 v84, v159
	v_mov_b32_e32 v85, v159
	v_mov_b32_e32 v86, v159
	v_mov_b32_e32 v87, v159
	v_mov_b32_e32 v88, v159
	v_mov_b32_e32 v89, v159
	v_mov_b32_e32 v90, v159
	v_mov_b32_e32 v91, v159
	v_mov_b32_e32 v92, v159
	v_mov_b32_e32 v93, v159
	v_mov_b32_e32 v94, v159
	v_mov_b32_e32 v95, v159
	v_mov_b32_e32 v96, v159
	v_mov_b32_e32 v97, v159
	v_mov_b32_e32 v98, v159
	v_mov_b32_e32 v99, v159
	v_mov_b32_e32 v100, v159
	v_mov_b32_e32 v101, v159
	v_mov_b32_e32 v102, v159
	v_mov_b32_e32 v103, v159
	v_mov_b32_e32 v104, v159
	v_mov_b32_e32 v105, v159
	v_mov_b32_e32 v106, v159
	v_mov_b32_e32 v107, v159
	v_mov_b32_e32 v108, v159
	v_mov_b32_e32 v109, v159
	v_mov_b32_e32 v110, v159
	v_mov_b32_e32 v111, v159
	v_mov_b32_e32 v112, v159
	v_mov_b32_e32 v113, v159
	v_mov_b32_e32 v114, v159
	v_mov_b32_e32 v115, v159
	v_mov_b32_e32 v116, v159
	v_mov_b32_e32 v117, v159
	v_mov_b32_e32 v118, v159
	v_mov_b32_e32 v119, v159
	v_mov_b32_e32 v120, v159
	v_mov_b32_e32 v121, v159
	v_mov_b32_e32 v122, v159
	v_mov_b32_e32 v123, v159
	v_mov_b32_e32 v124, v159
	v_mov_b32_e32 v125, v159
	v_mov_b32_e32 v126, v159
	v_mov_b32_e32 v127, v159
	v_mov_b32_e32 v128, v159
	v_mov_b32_e32 v129, v159
	s_barrier
	s_branch .LBB0_2618

.LBB0_2625:
	v_add_u32_e32 v142, s57, v161
	ds_read_b128 v[130:133], v142
	ds_read_b128 v[134:137], v142 offset:1024
	ds_read_b128 v[138:141], v142 offset:2048
	ds_read_b128 v[142:145], v142 offset:3072
	s_add_u32 s18, s38, 0xfffc0080
	s_addc_u32 s19, s39, -1
	s_cmp_eq_u32 s72, 4
	s_cselect_b32 s19, s25, s19
	s_cselect_b32 s18, s68, s18
	s_cselect_b32 s43, s17, s71
	s_cselect_b32 s42, s69, s70
	v_lshl_add_u64 v[204:205], s[38:39], 0, v[164:165]
	s_add_i32 m0, s50, 0xc000
	ds_read_b128 v[146:149], v171
	ds_read_b128 v[176:179], v171 offset:1024
	ds_read_b128 v[180:183], v171 offset:2048
	ds_read_b128 v[184:187], v171 offset:3072
	ds_read_b128 v[188:191], v171 offset:4096
	ds_read_b128 v[192:195], v171 offset:5120
	ds_read_b128 v[196:199], v171 offset:6144
	ds_read_b128 v[200:203], v171 offset:7168
	global_load_lds_dwordx4 v[204:205], off
	v_lshl_add_u64 v[204:205], s[38:39], 0, v[166:167]
	s_add_i32 m0, s50, 0xe000
	s_nop 0
	global_load_lds_dwordx4 v[204:205], off
	v_add_u32_e32 v158, s60, v161
	ds_read_b128 v[204:207], v158
	ds_read_b128 v[208:211], v158 offset:1024
	ds_read_b128 v[212:215], v158 offset:2048
	ds_read_b128 v[216:219], v158 offset:3072
	s_waitcnt vmcnt(8)
	s_waitcnt lgkmcnt(0)
	s_setprio 1
	s_barrier
	v_mfma_f32_16x16x32_bf16 v[126:129], v[130:133], v[146:149], v[126:129]
	v_mfma_f32_16x16x32_bf16 v[122:125], v[138:141], v[146:149], v[122:125]
	v_mfma_f32_16x16x32_bf16 v[118:121], v[130:133], v[180:183], v[118:121]
	v_mfma_f32_16x16x32_bf16 v[114:117], v[138:141], v[180:183], v[114:117]
	v_mfma_f32_16x16x32_bf16 v[110:113], v[130:133], v[188:191], v[110:113]
	v_mfma_f32_16x16x32_bf16 v[106:109], v[138:141], v[188:191], v[106:109]
	v_mfma_f32_16x16x32_bf16 v[102:105], v[130:133], v[196:199], v[102:105]
	v_mfma_f32_16x16x32_bf16 v[98:101], v[138:141], v[196:199], v[98:101]
	v_mfma_f32_16x16x32_bf16 v[126:129], v[134:137], v[176:179], v[126:129]
	v_mfma_f32_16x16x32_bf16 v[122:125], v[142:145], v[176:179], v[122:125]
	v_mfma_f32_16x16x32_bf16 v[118:121], v[134:137], v[184:187], v[118:121]
	v_mfma_f32_16x16x32_bf16 v[114:117], v[142:145], v[184:187], v[114:117]
	v_mfma_f32_16x16x32_bf16 v[110:113], v[134:137], v[192:195], v[110:113]
	v_mfma_f32_16x16x32_bf16 v[106:109], v[142:145], v[192:195], v[106:109]
	v_mfma_f32_16x16x32_bf16 v[102:105], v[134:137], v[200:203], v[102:105]
	v_mfma_f32_16x16x32_bf16 v[98:101], v[142:145], v[200:203], v[98:101]
	v_mfma_f32_16x16x32_bf16 v[94:97], v[204:207], v[146:149], v[94:97]
	v_mfma_f32_16x16x32_bf16 v[90:93], v[212:215], v[146:149], v[90:93]
	v_mfma_f32_16x16x32_bf16 v[86:89], v[204:207], v[180:183], v[86:89]
	v_mfma_f32_16x16x32_bf16 v[82:85], v[212:215], v[180:183], v[82:85]
	v_mfma_f32_16x16x32_bf16 v[78:81], v[204:207], v[188:191], v[78:81]
	v_mfma_f32_16x16x32_bf16 v[74:77], v[212:215], v[188:191], v[74:77]
	v_mfma_f32_16x16x32_bf16 v[70:73], v[204:207], v[196:199], v[70:73]
	v_mfma_f32_16x16x32_bf16 v[66:69], v[212:215], v[196:199], v[66:69]
	v_mfma_f32_16x16x32_bf16 v[94:97], v[208:211], v[176:179], v[94:97]
	v_mfma_f32_16x16x32_bf16 v[90:93], v[216:219], v[176:179], v[90:93]
	v_mfma_f32_16x16x32_bf16 v[86:89], v[208:211], v[184:187], v[86:89]
	v_mfma_f32_16x16x32_bf16 v[82:85], v[216:219], v[184:187], v[82:85]
	v_mfma_f32_16x16x32_bf16 v[78:81], v[208:211], v[192:195], v[78:81]
	v_mfma_f32_16x16x32_bf16 v[74:77], v[216:219], v[192:195], v[74:77]
	v_mfma_f32_16x16x32_bf16 v[70:73], v[208:211], v[200:203], v[70:73]
	v_mfma_f32_16x16x32_bf16 v[66:69], v[216:219], v[200:203], v[66:69]
	s_barrier
	s_setprio 0
	s_add_i32 s20, s57, s48
	v_lshl_add_u64 v[220:221], s[42:43], 0, v[152:153]
	s_mov_b32 m0, s20
	s_nop 0
	global_load_lds_dwordx4 v[220:221], off
	v_lshl_add_u64 v[222:223], s[42:43], 0, v[156:157]
	s_add_i32 m0, s20, 0x2000
	s_nop 0
	global_load_lds_dwordx4 v[222:223], off
	s_mov_b32 m0, s50
	v_lshl_add_u64 v[224:225], s[18:19], 0, v[150:151]
	ds_read_b128 v[146:149], v171 offset:16384
	ds_read_b128 v[176:179], v171 offset:17408
	ds_read_b128 v[180:183], v171 offset:18432
	ds_read_b128 v[184:187], v171 offset:19456
	ds_read_b128 v[188:191], v171 offset:20480
	ds_read_b128 v[192:195], v171 offset:21504
	ds_read_b128 v[196:199], v171 offset:22528
	ds_read_b128 v[200:203], v171 offset:23552
	global_load_lds_dwordx4 v[224:225], off
	v_lshl_add_u64 v[226:227], s[18:19], 0, v[154:155]
	s_mov_b32 m0, s51
	s_nop 0
	global_load_lds_dwordx4 v[226:227], off
	s_add_u32 s20, s42, 0x40000
	s_addc_u32 s21, s43, 0
	s_add_i32 s73, s60, s48
	v_lshl_add_u64 v[246:247], s[20:21], 0, v[152:153]
	s_mov_b32 m0, s73
	s_nop 0
	global_load_lds_dwordx4 v[246:247], off
	v_lshl_add_u64 v[246:247], s[20:21], 0, v[156:157]
	s_add_i32 m0, s73, 0x2000
	s_nop 0
	global_load_lds_dwordx4 v[246:247], off
	s_waitcnt vmcnt(8)
	s_waitcnt lgkmcnt(0)
	s_setprio 1
	s_barrier
	v_mfma_f32_16x16x32_bf16 v[62:65], v[130:133], v[146:149], v[62:65]
	v_mfma_f32_16x16x32_bf16 v[58:61], v[138:141], v[146:149], v[58:61]
	v_mfma_f32_16x16x32_bf16 v[54:57], v[130:133], v[180:183], v[54:57]
	v_mfma_f32_16x16x32_bf16 v[50:53], v[138:141], v[180:183], v[50:53]
	v_mfma_f32_16x16x32_bf16 v[46:49], v[130:133], v[188:191], v[46:49]
	v_mfma_f32_16x16x32_bf16 v[42:45], v[138:141], v[188:191], v[42:45]
	v_mfma_f32_16x16x32_bf16 v[38:41], v[130:133], v[196:199], v[38:41]
	v_mfma_f32_16x16x32_bf16 v[34:37], v[138:141], v[196:199], v[34:37]
	v_mfma_f32_16x16x32_bf16 v[62:65], v[134:137], v[176:179], v[62:65]
	v_mfma_f32_16x16x32_bf16 v[58:61], v[142:145], v[176:179], v[58:61]
	v_mfma_f32_16x16x32_bf16 v[54:57], v[134:137], v[184:187], v[54:57]
	v_mfma_f32_16x16x32_bf16 v[50:53], v[142:145], v[184:187], v[50:53]
	v_mfma_f32_16x16x32_bf16 v[46:49], v[134:137], v[192:195], v[46:49]
	v_mfma_f32_16x16x32_bf16 v[42:45], v[142:145], v[192:195], v[42:45]
	v_mfma_f32_16x16x32_bf16 v[38:41], v[134:137], v[200:203], v[38:41]
	v_mfma_f32_16x16x32_bf16 v[34:37], v[142:145], v[200:203], v[34:37]
	v_mfma_f32_16x16x32_bf16 v[30:33], v[204:207], v[146:149], v[30:33]
	v_mfma_f32_16x16x32_bf16 v[26:29], v[212:215], v[146:149], v[26:29]
	v_mfma_f32_16x16x32_bf16 v[22:25], v[204:207], v[180:183], v[22:25]
	v_mfma_f32_16x16x32_bf16 v[18:21], v[212:215], v[180:183], v[18:21]
	v_mfma_f32_16x16x32_bf16 v[14:17], v[204:207], v[188:191], v[14:17]
	v_mfma_f32_16x16x32_bf16 v[10:13], v[212:215], v[188:191], v[10:13]
	v_mfma_f32_16x16x32_bf16 v[6:9], v[204:207], v[196:199], v[6:9]
	v_mfma_f32_16x16x32_bf16 v[2:5], v[212:215], v[196:199], v[2:5]
	v_mfma_f32_16x16x32_bf16 v[30:33], v[208:211], v[176:179], v[30:33]
	v_mfma_f32_16x16x32_bf16 v[26:29], v[216:219], v[176:179], v[26:29]
	v_mfma_f32_16x16x32_bf16 v[22:25], v[208:211], v[184:187], v[22:25]
	v_mfma_f32_16x16x32_bf16 v[18:21], v[216:219], v[184:187], v[18:21]
	v_mfma_f32_16x16x32_bf16 v[14:17], v[208:211], v[192:195], v[14:17]
	v_mfma_f32_16x16x32_bf16 v[10:13], v[216:219], v[192:195], v[10:13]
	v_mfma_f32_16x16x32_bf16 v[6:9], v[208:211], v[200:203], v[6:9]
	v_mfma_f32_16x16x32_bf16 v[2:5], v[216:219], v[200:203], v[2:5]
	s_barrier
	s_setprio 0
	s_add_i32 s20, 0, 0x18000
	v_add_u32_e32 v142, s20, v161
	ds_read_b128 v[130:133], v142
	ds_read_b128 v[134:137], v142 offset:1024
	ds_read_b128 v[138:141], v142 offset:2048
	ds_read_b128 v[142:145], v142 offset:3072
	s_add_u32 s18, s18, 0x40000
	s_addc_u32 s19, s19, 0
	s_mov_b32 m0, s52
	v_lshl_add_u64 v[204:205], s[18:19], 0, v[150:151]
	ds_read_b128 v[146:149], v171 offset:32768
	ds_read_b128 v[176:179], v171 offset:33792
	ds_read_b128 v[180:183], v171 offset:34816
	ds_read_b128 v[184:187], v171 offset:35840
	ds_read_b128 v[188:191], v171 offset:36864
	ds_read_b128 v[192:195], v171 offset:37888
	ds_read_b128 v[196:199], v171 offset:38912
	ds_read_b128 v[200:203], v171 offset:39936
	global_load_lds_dwordx4 v[204:205], off
	v_lshl_add_u64 v[204:205], s[18:19], 0, v[154:155]
	s_mov_b32 m0, s53
	s_nop 0
	global_load_lds_dwordx4 v[204:205], off
	s_add_i32 s21, 0, 0x1c000
	v_add_u32_e32 v158, s21, v161
	ds_read_b128 v[204:207], v158
	ds_read_b128 v[208:211], v158 offset:1024
	ds_read_b128 v[212:215], v158 offset:2048
	ds_read_b128 v[216:219], v158 offset:3072
	s_waitcnt vmcnt(8)
	s_waitcnt lgkmcnt(0)
	s_setprio 1
	s_barrier
	v_mfma_f32_16x16x32_bf16 v[126:129], v[130:133], v[146:149], v[126:129]
	v_mfma_f32_16x16x32_bf16 v[122:125], v[138:141], v[146:149], v[122:125]
	v_mfma_f32_16x16x32_bf16 v[118:121], v[130:133], v[180:183], v[118:121]
	v_mfma_f32_16x16x32_bf16 v[114:117], v[138:141], v[180:183], v[114:117]
	v_mfma_f32_16x16x32_bf16 v[110:113], v[130:133], v[188:191], v[110:113]
	v_mfma_f32_16x16x32_bf16 v[106:109], v[138:141], v[188:191], v[106:109]
	v_mfma_f32_16x16x32_bf16 v[102:105], v[130:133], v[196:199], v[102:105]
	v_mfma_f32_16x16x32_bf16 v[98:101], v[138:141], v[196:199], v[98:101]
	v_mfma_f32_16x16x32_bf16 v[126:129], v[134:137], v[176:179], v[126:129]
	v_mfma_f32_16x16x32_bf16 v[122:125], v[142:145], v[176:179], v[122:125]
	v_mfma_f32_16x16x32_bf16 v[118:121], v[134:137], v[184:187], v[118:121]
	v_mfma_f32_16x16x32_bf16 v[114:117], v[142:145], v[184:187], v[114:117]
	v_mfma_f32_16x16x32_bf16 v[110:113], v[134:137], v[192:195], v[110:113]
	v_mfma_f32_16x16x32_bf16 v[106:109], v[142:145], v[192:195], v[106:109]
	v_mfma_f32_16x16x32_bf16 v[102:105], v[134:137], v[200:203], v[102:105]
	v_mfma_f32_16x16x32_bf16 v[98:101], v[142:145], v[200:203], v[98:101]
	v_mfma_f32_16x16x32_bf16 v[94:97], v[204:207], v[146:149], v[94:97]
	v_mfma_f32_16x16x32_bf16 v[90:93], v[212:215], v[146:149], v[90:93]
	v_mfma_f32_16x16x32_bf16 v[86:89], v[204:207], v[180:183], v[86:89]
	v_mfma_f32_16x16x32_bf16 v[82:85], v[212:215], v[180:183], v[82:85]
	v_mfma_f32_16x16x32_bf16 v[78:81], v[204:207], v[188:191], v[78:81]
	v_mfma_f32_16x16x32_bf16 v[74:77], v[212:215], v[188:191], v[74:77]
	v_mfma_f32_16x16x32_bf16 v[70:73], v[204:207], v[196:199], v[70:73]
	v_mfma_f32_16x16x32_bf16 v[66:69], v[212:215], v[196:199], v[66:69]
	v_mfma_f32_16x16x32_bf16 v[94:97], v[208:211], v[176:179], v[94:97]
	v_mfma_f32_16x16x32_bf16 v[90:93], v[216:219], v[176:179], v[90:93]
	v_mfma_f32_16x16x32_bf16 v[86:89], v[208:211], v[184:187], v[86:89]
	v_mfma_f32_16x16x32_bf16 v[82:85], v[216:219], v[184:187], v[82:85]
	v_mfma_f32_16x16x32_bf16 v[78:81], v[208:211], v[192:195], v[78:81]
	v_mfma_f32_16x16x32_bf16 v[74:77], v[216:219], v[192:195], v[74:77]
	v_mfma_f32_16x16x32_bf16 v[70:73], v[208:211], v[200:203], v[70:73]
	v_mfma_f32_16x16x32_bf16 v[66:69], v[216:219], v[200:203], v[66:69]
	s_barrier
	s_setprio 0
	s_add_i32 s18, s20, s48
	v_lshl_add_u64 v[220:221], v[220:221], 0, s[6:7]
	s_mov_b32 m0, s18
	s_nop 0
	global_load_lds_dwordx4 v[220:221], off
	v_lshl_add_u64 v[220:221], v[222:223], 0, s[6:7]
	s_add_i32 m0, s18, 0x2000
	s_nop 0
	global_load_lds_dwordx4 v[220:221], off
	s_mov_b32 m0, s55
	v_lshl_add_u64 v[220:221], v[224:225], 0, s[6:7]
	ds_read_b128 v[146:149], v171 offset:49152
	ds_read_b128 v[176:179], v171 offset:50176
	ds_read_b128 v[180:183], v171 offset:51200
	ds_read_b128 v[184:187], v171 offset:52224
	ds_read_b128 v[188:191], v171 offset:53248
	ds_read_b128 v[192:195], v171 offset:54272
	ds_read_b128 v[196:199], v171 offset:55296
	ds_read_b128 v[200:203], v171 offset:56320
	global_load_lds_dwordx4 v[220:221], off
	v_lshl_add_u64 v[220:221], v[226:227], 0, s[6:7]
	s_mov_b32 m0, s56
	s_nop 0
	global_load_lds_dwordx4 v[220:221], off
	s_add_u32 s18, s42, 0x40080
	s_addc_u32 s19, s43, 0
	s_add_i32 s20, s21, s48
	v_lshl_add_u64 v[248:249], s[18:19], 0, v[152:153]
	s_mov_b32 m0, s20
	s_nop 0
	global_load_lds_dwordx4 v[248:249], off
	v_lshl_add_u64 v[248:249], s[18:19], 0, v[156:157]
	s_add_i32 m0, s20, 0x2000
	s_nop 0
	global_load_lds_dwordx4 v[248:249], off
	s_waitcnt vmcnt(8)
	s_waitcnt lgkmcnt(0)
	s_setprio 1
	s_barrier
	v_mfma_f32_16x16x32_bf16 v[62:65], v[130:133], v[146:149], v[62:65]
	v_mfma_f32_16x16x32_bf16 v[58:61], v[138:141], v[146:149], v[58:61]
	v_mfma_f32_16x16x32_bf16 v[54:57], v[130:133], v[180:183], v[54:57]
	v_mfma_f32_16x16x32_bf16 v[50:53], v[138:141], v[180:183], v[50:53]
	v_mfma_f32_16x16x32_bf16 v[46:49], v[130:133], v[188:191], v[46:49]
	v_mfma_f32_16x16x32_bf16 v[42:45], v[138:141], v[188:191], v[42:45]
	v_mfma_f32_16x16x32_bf16 v[38:41], v[130:133], v[196:199], v[38:41]
	v_mfma_f32_16x16x32_bf16 v[34:37], v[138:141], v[196:199], v[34:37]
	v_mfma_f32_16x16x32_bf16 v[62:65], v[134:137], v[176:179], v[62:65]
	v_mfma_f32_16x16x32_bf16 v[58:61], v[142:145], v[176:179], v[58:61]
	v_mfma_f32_16x16x32_bf16 v[54:57], v[134:137], v[184:187], v[54:57]
	v_mfma_f32_16x16x32_bf16 v[50:53], v[142:145], v[184:187], v[50:53]
	v_mfma_f32_16x16x32_bf16 v[46:49], v[134:137], v[192:195], v[46:49]
	v_mfma_f32_16x16x32_bf16 v[42:45], v[142:145], v[192:195], v[42:45]
	v_mfma_f32_16x16x32_bf16 v[38:41], v[134:137], v[200:203], v[38:41]
	v_mfma_f32_16x16x32_bf16 v[34:37], v[142:145], v[200:203], v[34:37]
	v_mfma_f32_16x16x32_bf16 v[30:33], v[204:207], v[146:149], v[30:33]
	v_mfma_f32_16x16x32_bf16 v[26:29], v[212:215], v[146:149], v[26:29]
	v_mfma_f32_16x16x32_bf16 v[22:25], v[204:207], v[180:183], v[22:25]
	v_mfma_f32_16x16x32_bf16 v[18:21], v[212:215], v[180:183], v[18:21]
	v_mfma_f32_16x16x32_bf16 v[14:17], v[204:207], v[188:191], v[14:17]
	v_mfma_f32_16x16x32_bf16 v[10:13], v[212:215], v[188:191], v[10:13]
	v_mfma_f32_16x16x32_bf16 v[6:9], v[204:207], v[196:199], v[6:9]
	v_mfma_f32_16x16x32_bf16 v[2:5], v[212:215], v[196:199], v[2:5]
	v_mfma_f32_16x16x32_bf16 v[30:33], v[208:211], v[176:179], v[30:33]
	v_mfma_f32_16x16x32_bf16 v[26:29], v[216:219], v[176:179], v[26:29]
	v_mfma_f32_16x16x32_bf16 v[22:25], v[208:211], v[184:187], v[22:25]
	v_mfma_f32_16x16x32_bf16 v[18:21], v[216:219], v[184:187], v[18:21]
	v_mfma_f32_16x16x32_bf16 v[14:17], v[208:211], v[192:195], v[14:17]
	v_mfma_f32_16x16x32_bf16 v[10:13], v[216:219], v[192:195], v[10:13]
	v_mfma_f32_16x16x32_bf16 v[6:9], v[208:211], v[200:203], v[6:9]
	v_mfma_f32_16x16x32_bf16 v[2:5], v[216:219], v[200:203], v[2:5]
	s_barrier
	s_setprio 0
	s_add_i32 s72, s72, 2
	s_add_u32 s38, s38, 0x100
	s_addc_u32 s39, s39, 0
	s_add_u32 s70, s70, 0x100
	s_addc_u32 s71, s71, 0
	s_cmp_gt_u32 s72, 5
	s_cbranch_scc0 .LBB0_2625
	s_cmp_lg_u32 s41, 1
	v_lshl_add_u32 v182, s40, 8, v1
	s_cselect_b64 s[38:39], -1, 0
	s_lshl_b32 s40, s67, 8
	v_or_b32_e32 v180, 16, v182
	v_or_b32_e32 v178, 32, v182
	v_or_b32_e32 v176, 48, v182
	s_ashr_i32 s41, s40, 31
	s_mov_b64 s[18:19], -1
	s_and_b64 vcc, exec, s[38:39]
	v_ashrrev_i32_e32 v183, 31, v182
	v_lshlrev_b32_e32 v158, 1, v160
	v_ashrrev_i32_e32 v181, 31, v180
	v_ashrrev_i32_e32 v179, 31, v178
	v_ashrrev_i32_e32 v177, 31, v176
	s_cbranch_vccnz .LBB0_2629
	s_andn2_b64 vcc, exec, s[18:19]
	s_cbranch_vccz .LBB0_2630

.LBB0_2836:
	s_add_u32 s6, s30, 0x1b00000
	s_addc_u32 s7, s31, 0
	s_add_u32 s8, s30, 0x5b00000
	s_mov_b64 s[10:11], 0x80
	s_addc_u32 s9, s31, 0
	s_and_b32 s61, s2, 3
	s_add_i32 m0, s53, 0x18000
	v_lshl_add_u64 v[8:9], v[8:9], 0, s[10:11]
	s_ashr_i32 s57, s22, 31
	s_ashr_i32 s60, s86, 31
	s_lshl_b32 s5, s4, 13
	s_lshl_b32 s12, s61, 12
	s_waitcnt vmcnt(0)
	s_barrier
	global_load_lds_dwordx4 v[8:9], off
	v_lshl_add_u64 v[6:7], v[6:7], 0, s[10:11]
	s_add_i32 m0, s53, 0x1a000
	s_add_i32 s62, s53, 0x8000
	s_add_i32 s63, s53, 0xa000
	global_load_lds_dwordx4 v[6:7], off
	v_lshl_add_u64 v[4:5], v[4:5], 0, s[10:11]
	s_mov_b32 m0, s62
	s_add_u32 s2, s46, 0x40080
	global_load_lds_dwordx4 v[4:5], off
	v_lshl_add_u64 v[2:3], v[2:3], 0, s[10:11]
	s_mov_b32 m0, s63
	s_addc_u32 s3, s47, 0
	global_load_lds_dwordx4 v[2:3], off
	s_add_i32 m0, s53, 0x1c000
	v_lshl_add_u64 v[2:3], s[2:3], 0, v[176:177]
	global_load_lds_dwordx4 v[2:3], off
	v_lshl_add_u64 v[2:3], s[2:3], 0, v[180:181]
	s_add_i32 m0, s53, 0x1e000
	v_bfe_u32 v1, v170, 4, 2
	global_load_lds_dwordx4 v[2:3], off
	v_lshlrev_b32_e32 v3, 3, v1
	v_and_b32_e32 v2, 15, v170
	v_lshlrev_b32_e32 v4, 4, v1
	v_lshlrev_b32_e32 v5, 6, v170
	s_movk_i32 s2, 0x3c0
	v_lshl_or_b32 v184, s61, 5, v3
	v_lshlrev_b32_e32 v3, 8, v170
	v_and_or_b32 v5, v5, s2, v4
	v_cmp_eq_u32_e64 s[2:3], 0, v1
	v_lshl_or_b32 v1, s4, 6, v2
	v_lshl_or_b32 v2, v2, 6, v4
	v_and_b32_e32 v3, 0x38000, v3
	v_lshlrev_b32_e32 v4, 11, v231
	v_lshlrev_b32_e32 v6, 2, v170
	v_or3_b32 v3, v10, v3, v4
	v_and_b32_e32 v6, 32, v6
	v_add_u32_e32 v188, v3, v11
	v_lshlrev_b32_e32 v3, 4, v12
	v_bitop3_b32 v2, v2, s5, v6 bitop3:0xde
	s_waitcnt vmcnt(6)
	v_and_b32_e32 v3, 0x78000, v3
	v_bitop3_b32 v171, s12, v5, v6 bitop3:0xf6
	v_lshlrev_b32_e32 v182, 1, v184
	v_or3_b32 v3, v10, v3, v4
	s_add_i32 s65, 0, 0x10000
	v_add_u32_e32 v185, 0, v2
	s_add_i32 s66, 0, 0x14000
	v_mbcnt_lo_u32_b32 v2, -1, 0
	s_mov_b32 s64, s22
	v_lshl_add_u64 v[186:187], s[28:29], 0, v[182:183]
	v_mov_b32_e32 v189, v183
	v_add_u32_e32 v190, v3, v11
	v_mov_b32_e32 v191, v183
	v_mov_b64_e32 v[192:193], 0x200
	v_mov_b64_e32 v[194:195], 0x1ff
	v_add_u32_e32 v173, s65, v171
	v_add_u32_e32 v222, s66, v171
	s_mov_b64 s[12:13], 0x5000
	s_movk_i32 s67, 0x5000
	s_mov_b64 s[14:15], 0x5200
	s_mov_b64 s[16:17], 0x7000
	s_movk_i32 s68, 0x7000
	s_mov_b64 s[24:25], 0x7200
	v_mbcnt_hi_u32_b32 v223, -1, v2
	s_mov_b32 s69, 0
	s_barrier
	s_branch .LBB0_2838

.LBB0_3261:
	s_add_u32 s0, s30, 0x9b00000
	s_addc_u32 s1, s31, 0
	s_add_u32 s4, s30, 0x1a51800
	s_addc_u32 s5, s31, 0
	s_add_u32 s48, s30, 0x10f000
	s_addc_u32 s49, s31, 0
	s_mov_b64 s[6:7], 0x80
	s_add_u32 s10, s34, 0x40080
	v_lshl_add_u64 v[2:3], v[2:3], 0, s[6:7]
	s_addc_u32 s11, s35, 0
	s_add_i32 m0, s43, 0x18000
	v_lshl_add_u64 v[4:5], v[4:5], 0, s[6:7]
	s_waitcnt vmcnt(0)
	s_barrier
	global_load_lds_dwordx4 v[2:3], off
	s_add_i32 m0, s43, 0x1a000
	s_add_i32 s50, s43, 0x8000
	v_lshl_add_u64 v[6:7], v[6:7], 0, s[6:7]
	global_load_lds_dwordx4 v[4:5], off
	s_mov_b32 m0, s50
	s_add_i32 s51, s43, 0xa000
	v_lshl_add_u64 v[8:9], v[8:9], 0, s[6:7]
	global_load_lds_dwordx4 v[6:7], off
	s_mov_b32 m0, s51
	s_waitcnt vmcnt(0)
	v_lshl_add_u64 v[14:15], s[10:11], 0, v[150:151]
	global_load_lds_dwordx4 v[8:9], off
	s_add_i32 m0, s43, 0x1c000
	v_lshl_add_u64 v[16:17], s[10:11], 0, v[146:147]
	global_load_lds_dwordx4 v[14:15], off
	s_add_i32 m0, s43, 0x1e000
	v_bfe_u32 v1, v170, 4, 2
	global_load_lds_dwordx4 v[16:17], off
	v_lshlrev_b32_e32 v3, 3, v1
	v_lshlrev_b32_e32 v4, 4, v1
	v_lshlrev_b32_e32 v1, 6, v170
	s_movk_i32 s9, 0x3c0
	s_sext_i32_i16 s17, s2
	s_and_b32 s2, s8, 3
	v_and_b32_e32 v2, 15, v170
	v_and_or_b32 v5, v1, s9, v4
	v_lshlrev_b32_e32 v1, 2, v170
	v_lshl_or_b32 v156, s2, 5, v3
	v_lshlrev_b32_e32 v3, 8, v170
	v_and_b32_e32 v6, 32, v1
	v_lshl_or_b32 v1, s3, 6, v2
	v_lshl_or_b32 v2, v2, 6, v4
	v_and_b32_e32 v3, 0x38000, v3
	v_lshlrev_b32_e32 v4, 11, v231
	v_or3_b32 v3, v11, v3, v4
	s_lshl_b32 s3, s3, 13
	v_add_u32_e32 v158, v3, v12
	v_lshlrev_b32_e32 v3, 4, v10
	v_bitop3_b32 v2, v2, s3, v6 bitop3:0xde
	s_lshl_b32 s3, s2, 12
	s_waitcnt vmcnt(6)
	v_and_b32_e32 v3, 0x78000, v3
	v_bitop3_b32 v157, s3, v5, v6 bitop3:0xf6
	v_or3_b32 v3, v11, v3, v4
	s_add_i32 s54, 0, 0x10000
	s_add_i32 s55, 0, 0x14000
	s_ashr_i32 s52, s22, 31
	s_mov_b32 s53, s22
	v_mov_b32_e32 v159, v155
	v_add_u32_e32 v160, v3, v12
	v_mov_b32_e32 v161, v155
	v_mov_b64_e32 v[162:163], 0xb00
	v_mov_b64_e32 v[164:165], 0xaff
	v_add_u32_e32 v171, s54, v157
	v_add_u32_e32 v173, 0, v2
	v_add_u32_e32 v177, s55, v157
	s_movk_i32 s56, 0x1600
	s_barrier

.LBB0_3470:
	s_add_u32 s10, s30, 0x1b00000
	s_addc_u32 s11, s31, 0
	s_add_u32 s12, s30, 0x5d00000
	s_mov_b64 s[14:15], 0x80
	s_addc_u32 s13, s31, 0
	s_and_b32 s47, s1, 3
	s_add_i32 m0, s41, 0x18000
	v_lshl_add_u64 v[8:9], v[8:9], 0, s[14:15]
	s_ashr_i32 s45, s22, 31
	s_ashr_i32 s46, s86, 31
	s_lshl_b32 s1, s0, 13
	s_lshl_b32 s4, s47, 12
	s_waitcnt vmcnt(0)
	s_barrier
	global_load_lds_dwordx4 v[8:9], off
	v_lshl_add_u64 v[6:7], v[6:7], 0, s[14:15]
	s_add_i32 m0, s41, 0x1a000
	s_add_i32 s48, s41, 0x8000
	s_add_i32 s49, s41, 0xa000
	global_load_lds_dwordx4 v[6:7], off
	v_lshl_add_u64 v[4:5], v[4:5], 0, s[14:15]
	s_mov_b32 m0, s48
	s_add_u32 s2, s34, 0xb0080
	global_load_lds_dwordx4 v[4:5], off
	v_lshl_add_u64 v[2:3], v[2:3], 0, s[14:15]
	s_mov_b32 m0, s49
	s_addc_u32 s3, s35, 0
	global_load_lds_dwordx4 v[2:3], off
	s_add_i32 m0, s41, 0x1c000
	v_lshl_add_u64 v[2:3], s[2:3], 0, v[156:157]
	global_load_lds_dwordx4 v[2:3], off
	v_lshl_add_u64 v[2:3], s[2:3], 0, v[160:161]
	s_add_i32 m0, s41, 0x1e000
	v_bfe_u32 v1, v170, 4, 2
	global_load_lds_dwordx4 v[2:3], off
	v_and_b32_e32 v2, 15, v170
	v_lshlrev_b32_e32 v4, 4, v1
	v_lshlrev_b32_e32 v5, 6, v170
	s_movk_i32 s2, 0x3c0
	v_lshlrev_b32_e32 v6, 2, v170
	v_lshlrev_b32_e32 v3, 3, v1
	v_and_or_b32 v5, v5, s2, v4
	v_and_b32_e32 v6, 32, v6
	v_cmp_eq_u32_e64 s[2:3], 0, v1
	v_lshl_or_b32 v1, s0, 6, v2
	v_lshl_or_b32 v2, v2, 6, v4
	v_bitop3_b32 v2, v2, s1, v6 bitop3:0xde
	s_waitcnt vmcnt(6)
	v_lshl_or_b32 v164, s47, 5, v3
	v_add_u16_e32 v3, v12, v13
	v_bitop3_b32 v165, s4, v5, v6 bitop3:0xf6
	v_lshlrev_b32_e32 v162, 1, v164
	v_lshrrev_b16_e32 v3, 1, v3
	s_add_i32 s52, 0, 0x10000
	v_add_u32_e32 v210, 0, v2
	s_add_i32 s53, 0, 0x14000
	v_mbcnt_lo_u32_b32 v2, -1, 0
	s_mov_b32 s50, s22
	s_mov_b32 s51, 0x8000
	v_lshl_add_u64 v[166:167], s[28:29], 0, v[162:163]
	v_add_lshl_u32 v168, v11, v3, 1
	v_mov_b32_e32 v169, v163
	v_add_lshl_u32 v172, v10, v3, 1
	v_mov_b32_e32 v173, v163
	v_mov_b64_e32 v[174:175], 0x200
	v_mov_b64_e32 v[176:177], 0x1ff
	v_add_u32_e32 v171, s52, v165
	v_add_u32_e32 v211, s53, v165
	s_mov_b64 s[16:17], 0x8000
	v_mbcnt_hi_u32_b32 v212, -1, v2
	s_mov_b32 s54, 0
	s_barrier
	s_branch .LBB0_3472
